# band-prompt units (u>=2) moved to the hand-written pipelined tile loop (one barrier per tile, per-wave window via skeleton steps, far bias in the MFMA C operand, near-tile bias from the LDS table)
# speedup vs baseline: 1.0448x; 1.0323x over previous
.LBB0_812:
	s_and_b32 s0, s78, 0x3fffffc0
	v_lshlrev_b32_e32 v238, 2, v235
	v_lshrrev_b32_e32 v4, 2, v6
	s_lshl_b32 s0, s0, 2
	v_lshlrev_b32_e32 v2, 1, v6
	v_and_or_b32 v4, v4, 3, v238
	s_add_i32 s57, s0, 0
	s_lshl_b32 s0, s96, 5
	v_and_b32_e32 v2, 32, v2
	s_and_b32 s12, s0, 32
	v_lshl_add_u32 v4, v4, 6, 0
	s_add_i32 s57, s57, 0x14000
	s_add_i32 s43, s82, -2
	v_add3_u32 v241, v4, v2, v7
	v_add_u32_e32 v2, s12, v234
	s_waitcnt lgkmcnt(0)
	v_mov_b32_e32 v67, v66
	v_mov_b32_e32 v68, v66
	v_mov_b32_e32 v69, v66
	v_mov_b32_e32 v70, v66
	v_mov_b32_e32 v71, v66
	v_mov_b32_e32 v72, v66
	v_mov_b32_e32 v73, v66
	v_mov_b32_e32 v74, v66
	v_mov_b32_e32 v75, v66
	v_mov_b32_e32 v76, v66
	v_mov_b32_e32 v77, v66
	v_mov_b32_e32 v78, v66
	v_mov_b32_e32 v79, v66
	v_mov_b32_e32 v80, v66
	v_mov_b32_e32 v81, v66
	s_cmp_ge_i32 s16, s17
	v_cmp_gt_u32_e64 s[0:1], 32, v233
	v_lshl_add_u32 v237, v238, 2, s57
	v_sub_u32_e32 v243, v2, v238
	s_cbranch_scc1 .LBB0_865
	s_cmpk_gt_u32 s78, 0xff
	s_cselect_b64 s[88:89], -1, 0
	s_cmpk_lt_u32 s78, 0x100
	v_lshlrev_b32_e32 v2, 2, v243
	s_cselect_b64 s[90:91], -1, 0
	v_lshl_add_u32 v2, s29, 8, v2
	s_lshl_b32 s12, s16, 8
	v_subrev_u32_e32 v2, s12, v2
	v_mov_b32_e32 v16, v3
	v_mov_b32_e32 v17, v3
	v_add_u32_e32 v245, s52, v2
	s_sub_i32 s79, s16, s82
	v_mov_b32_e32 v2, v3
	v_mov_b32_e32 v4, v3
	v_mov_b32_e32 v5, v3
	v_mov_b32_e32 v6, v3
	v_mov_b32_e32 v7, v3
	v_mov_b32_e32 v8, v3
	v_mov_b32_e32 v9, v3
	v_mov_b32_e32 v10, v3
	v_mov_b32_e32 v11, v3
	v_mov_b32_e32 v12, v3
	v_mov_b32_e32 v13, v3
	v_mov_b32_e32 v14, v3
	v_mov_b32_e32 v15, v3
	v_mov_b32_e32 v162, 0
	v_mov_b64_e32 v[64:65], v[16:17]
	v_mov_b64_e32 v[48:49], v[16:17]
	v_mov_b64_e32 v[96:97], v[16:17]
	v_mov_b64_e32 v[112:113], v[80:81]
	v_lshl_add_u32 v244, v234, 2, s57
	s_sub_i32 s26, s29, s16
	s_add_i32 s79, s79, 1
	s_mov_b32 s83, 0
	s_mov_b64 s[86:87], -1
	v_mov_b32_e32 v242, 0
	s_movk_i32 s80, 0x6000
	v_mov_b64_e32 v[62:63], v[14:15]
	v_mov_b64_e32 v[60:61], v[12:13]
	v_mov_b64_e32 v[58:59], v[10:11]
	v_mov_b64_e32 v[56:57], v[8:9]
	v_mov_b64_e32 v[54:55], v[6:7]
	v_mov_b64_e32 v[52:53], v[4:5]
	v_mov_b64_e32 v[50:51], v[2:3]
	v_mov_b64_e32 v[46:47], v[14:15]
	v_mov_b64_e32 v[44:45], v[12:13]
	v_mov_b64_e32 v[42:43], v[10:11]
	v_mov_b64_e32 v[40:41], v[8:9]
	v_mov_b64_e32 v[38:39], v[6:7]
	v_mov_b64_e32 v[36:37], v[4:5]
	v_mov_b64_e32 v[34:35], v[2:3]
	v_mov_b32_e32 v240, 0
	v_mov_b64_e32 v[94:95], v[14:15]
	v_mov_b64_e32 v[92:93], v[12:13]
	v_mov_b64_e32 v[90:91], v[10:11]
	v_mov_b64_e32 v[88:89], v[8:9]
	v_mov_b64_e32 v[86:87], v[6:7]
	v_mov_b64_e32 v[84:85], v[4:5]
	v_mov_b64_e32 v[82:83], v[2:3]
	v_mov_b64_e32 v[110:111], v[78:79]
	v_mov_b64_e32 v[108:109], v[76:77]
	v_mov_b64_e32 v[106:107], v[74:75]
	v_mov_b64_e32 v[104:105], v[72:73]
	v_mov_b64_e32 v[102:103], v[70:71]
	v_mov_b64_e32 v[100:101], v[68:69]
	v_mov_b64_e32 v[98:99], v[66:67]
	v_mov_b32_e32 v163, v162
	v_mov_b32_e32 v164, v162
	v_mov_b32_e32 v165, v162
	v_mov_b32_e32 v166, v162
	v_mov_b32_e32 v167, v162
	v_mov_b32_e32 v168, v162
	v_mov_b32_e32 v169, v162
	v_mov_b32_e32 v170, v162
	v_mov_b32_e32 v171, v162
	v_mov_b32_e32 v172, v162
	v_mov_b32_e32 v173, v162
	v_mov_b32_e32 v174, v162
	v_mov_b32_e32 v175, v162
	v_mov_b32_e32 v176, v162
	v_mov_b32_e32 v177, v162
	v_mov_b32_e32 v178, v162
	v_mov_b32_e32 v179, v162
	v_mov_b32_e32 v180, v162
	v_mov_b32_e32 v181, v162
	v_mov_b32_e32 v182, v162
	v_mov_b32_e32 v183, v162
	v_mov_b32_e32 v184, v162
	v_mov_b32_e32 v185, v162
	v_mov_b32_e32 v186, v162
	v_mov_b32_e32 v187, v162
	v_mov_b32_e32 v188, v162
	v_mov_b32_e32 v189, v162
	v_mov_b32_e32 v190, v162
	v_mov_b32_e32 v191, v162
	v_mov_b32_e32 v192, v162
	v_mov_b32_e32 v193, v162
	s_sub_i32 s0, s82, s16
	s_cmp_eq_u32 s0, 12
	s_cbranch_scc1 .Lbd_entry
	s_branch .LBB0_816
.Lbd_entry:
	s_mov_b32 s30, 0x20000
	s_mov_b32 s31, 0
	s_lshr_b32 s80, s96, 1
	s_mov_b32 s79, 0
	v_mov_b32_e32 v23, v66
	v_lshl_add_u32 v29, v243, 2, s52
	s_add_i32 s0, s16, 4
	s_lshl_b32 s0, s0, 17
	s_mov_b32 s1, 0
	v_lshl_add_u64 v[24:25], v[226:227], 0, s[0:1]
	s_add_i32 s0, s16, 3
	s_lshl_b32 s0, s0, 17
	v_lshl_add_u64 v[26:27], v[228:229], 0, s[0:1]
	s_cmp_lt_u32 s96, 4
	s_cbranch_scc0 .Lbd_aligned
	s_waitcnt vmcnt(2)
	s_barrier
	v_lshl_add_u64 v[10:11], v[226:227], 0, s[0:1]
	s_add_u32 m0, s71, 0x9000
	s_nop 0
	global_load_lds_dwordx4 v[10:11], off
.Lbd_aligned:
	s_waitcnt lgkmcnt(0)
	s_cmp_eq_u32 s80, 0
	s_cbranch_scc0 .Lbd_lead
	v_mov_b32_e32 v2, v239
	ds_read_b128 v[194:197], v2
	ds_read_b128 v[198:201], v2 offset:512
	ds_read_b128 v[202:205], v2 offset:2048
	ds_read_b128 v[206:209], v2 offset:2560
	ds_read_b128 v[210:213], v2 offset:4096
	ds_read_b128 v[214:217], v2 offset:4608
	ds_read_b128 v[218:221], v2 offset:6144
	ds_read_b128 v[222:225], v2 offset:6656
	s_waitcnt lgkmcnt(0)
	v_mfma_f32_32x32x16_bf16 v[114:129], v[194:197], v[146:149], v[66:81]
	v_mfma_f32_32x32x16_bf16 v[130:145], v[198:201], v[146:149], v[66:81]
	v_mfma_f32_32x32x16_bf16 v[114:129], v[202:205], v[150:153], v[114:129]
	v_mfma_f32_32x32x16_bf16 v[130:145], v[206:209], v[150:153], v[130:145]
	v_mfma_f32_32x32x16_bf16 v[114:129], v[210:213], v[154:157], v[114:129]
	v_mfma_f32_32x32x16_bf16 v[130:145], v[214:217], v[154:157], v[130:145]
	v_mfma_f32_32x32x16_bf16 v[114:129], v[218:221], v[158:161], v[114:129]
	v_mfma_f32_32x32x16_bf16 v[130:145], v[222:225], v[158:161], v[130:145]
	v_add_u32_e32 v2, 0x3000, v239
	ds_read_b128 v[194:197], v2
	ds_read_b128 v[198:201], v2 offset:512
	ds_read_b128 v[202:205], v2 offset:2048
	ds_read_b128 v[206:209], v2 offset:2560
	ds_read_b128 v[210:213], v2 offset:4096
	ds_read_b128 v[214:217], v2 offset:4608
	ds_read_b128 v[218:221], v2 offset:6144
	ds_read_b128 v[222:225], v2 offset:6656
	s_nop 7
	v_max3_f32 v20, v114, v115, v116
	v_max3_f32 v21, v117, v118, v119
	v_max3_f32 v20, v20, v120, v121
	v_max3_f32 v21, v21, v122, v123
	v_max3_f32 v20, v20, v124, v125
	v_max3_f32 v21, v21, v126, v127
	v_max3_f32 v20, v20, v128, v129
	v_max3_f32 v21, v21, v130, v131
	v_max3_f32 v20, v20, v132, v133
	v_max3_f32 v21, v21, v134, v135
	v_max3_f32 v20, v20, v136, v137
	v_max3_f32 v21, v21, v138, v139
	v_max3_f32 v20, v20, v140, v141
	v_max3_f32 v21, v21, v142, v143
	v_max3_f32 v20, v20, v144, v145
	v_max_f32_e32 v20, v20, v21
	v_mov_b32_e32 v21, v20
	s_nop 1
	v_permlane32_swap_b32_e32 v20, v21
	v_max_f32_e32 v20, v20, v21
	v_max_f32_e32 v20, v20, v20
	v_mov_b32_e32 v242, v20
	v_xor_b32_e32 v82, 0x80000000, v20
	v_sub_f32_e32 v66, v23, v20
	v_mov_b32_e32 v83, v82
	v_mov_b32_e32 v67, v66
	v_mov_b32_e32 v84, v82
	v_mov_b32_e32 v68, v66
	v_mov_b32_e32 v85, v82
	v_mov_b32_e32 v69, v66
	v_mov_b32_e32 v86, v82
	v_mov_b32_e32 v70, v66
	v_mov_b32_e32 v87, v82
	v_mov_b32_e32 v71, v66
	v_mov_b32_e32 v88, v82
	v_mov_b32_e32 v72, v66
	v_mov_b32_e32 v89, v82
	v_mov_b32_e32 v73, v66
	v_mov_b32_e32 v90, v82
	v_mov_b32_e32 v74, v66
	v_mov_b32_e32 v91, v82
	v_mov_b32_e32 v75, v66
	v_mov_b32_e32 v92, v82
	v_mov_b32_e32 v76, v66
	v_mov_b32_e32 v93, v82
	v_mov_b32_e32 v77, v66
	v_mov_b32_e32 v94, v82
	v_mov_b32_e32 v78, v66
	v_mov_b32_e32 v95, v82
	v_mov_b32_e32 v79, v66
	v_mov_b32_e32 v96, v82
	v_mov_b32_e32 v80, v66
	v_mov_b32_e32 v97, v82
	v_mov_b32_e32 v81, v66
	v_sub_f32_e32 v114, v114, v20
	v_sub_f32_e32 v115, v115, v20
	v_sub_f32_e32 v116, v116, v20
	v_sub_f32_e32 v117, v117, v20
	v_sub_f32_e32 v118, v118, v20
	v_sub_f32_e32 v119, v119, v20
	v_sub_f32_e32 v120, v120, v20
	v_sub_f32_e32 v121, v121, v20
	v_sub_f32_e32 v122, v122, v20
	v_sub_f32_e32 v123, v123, v20
	v_sub_f32_e32 v124, v124, v20
	v_sub_f32_e32 v125, v125, v20
	v_sub_f32_e32 v126, v126, v20
	v_sub_f32_e32 v127, v127, v20
	v_sub_f32_e32 v128, v128, v20
	v_sub_f32_e32 v129, v129, v20
	v_sub_f32_e32 v130, v130, v20
	v_sub_f32_e32 v131, v131, v20
	v_sub_f32_e32 v132, v132, v20
	v_sub_f32_e32 v133, v133, v20
	v_sub_f32_e32 v134, v134, v20
	v_sub_f32_e32 v135, v135, v20
	v_sub_f32_e32 v136, v136, v20
	v_sub_f32_e32 v137, v137, v20
	v_sub_f32_e32 v138, v138, v20
	v_sub_f32_e32 v139, v139, v20
	v_sub_f32_e32 v140, v140, v20
	v_sub_f32_e32 v141, v141, v20
	v_sub_f32_e32 v142, v142, v20
	v_sub_f32_e32 v143, v143, v20
	v_sub_f32_e32 v144, v144, v20
	v_sub_f32_e32 v145, v145, v20
	s_branch .Lbd_far
.Lbd_lead:
	s_add_i32 s81, s80, -1
	s_cmp_lt_i32 s81, 1
	s_cbranch_scc1 .Lbd_qf
.Lbd_lead_loop:
	s_waitcnt vmcnt(2)
	s_cmp_lt_u32 s79, 9
	s_cbranch_scc1 .Lbd_w_1
	s_waitcnt vmcnt(0)
.Lbd_w_1:
	s_waitcnt lgkmcnt(0)
	s_barrier
	s_cmp_gt_u32 s79, 8
	s_cbranch_scc1 .Lbd_dk_3
	s_add_i32 s0, s79, 3
	s_and_b32 s0, s0, 3
	s_lshl_b32 s0, s0, 13
	s_add_u32 m0, s24, s0
	s_cmp_gt_u32 s79, 7
	global_load_lds_dwordx4 v[26:27], off
	v_lshl_add_u64 v[26:27], v[26:27], 0, s[30:31]
	s_cbranch_scc1 .Lbd_dk_3
	s_and_b32 s0, s79, 3
	s_mulk_i32 s0, 0x3000
	s_add_u32 m0, s71, s0
	s_nop 0
	global_load_lds_dwordx4 v[24:25], off
	v_lshl_add_u64 v[24:25], v[24:25], 0, s[30:31]
.Lbd_dk_3:
	s_add_i32 s79, s79, 1
	s_add_i32 s81, s81, -1
	s_cmp_gt_i32 s81, 0
	s_cbranch_scc1 .Lbd_lead_loop

.Lbd_dk_6:
	s_add_i32 s10, s79, 1
	s_and_b32 s10, s10, 3
	s_mulk_i32 s10, 0x3000
	v_add_u32_e32 v2, s10, v239
	ds_read_b128 v[194:197], v2
	ds_read_b128 v[198:201], v2 offset:512
	ds_read_b128 v[202:205], v2 offset:2048
	ds_read_b128 v[206:209], v2 offset:2560
	ds_read_b128 v[210:213], v2 offset:4096
	ds_read_b128 v[214:217], v2 offset:4608
	ds_read_b128 v[218:221], v2 offset:6144
	ds_read_b128 v[222:225], v2 offset:6656
	s_waitcnt lgkmcnt(0)
	v_mfma_f32_32x32x16_bf16 v[114:129], v[194:197], v[146:149], v[66:81]
	v_mfma_f32_32x32x16_bf16 v[130:145], v[198:201], v[146:149], v[66:81]
	v_mfma_f32_32x32x16_bf16 v[114:129], v[202:205], v[150:153], v[114:129]
	v_mfma_f32_32x32x16_bf16 v[130:145], v[206:209], v[150:153], v[130:145]
	v_mfma_f32_32x32x16_bf16 v[114:129], v[210:213], v[154:157], v[114:129]
	v_mfma_f32_32x32x16_bf16 v[130:145], v[214:217], v[154:157], v[130:145]
	v_mfma_f32_32x32x16_bf16 v[114:129], v[218:221], v[158:161], v[114:129]
	v_mfma_f32_32x32x16_bf16 v[130:145], v[222:225], v[158:161], v[130:145]
	s_add_i32 s10, s79, 2
	s_and_b32 s10, s10, 3
	s_mulk_i32 s10, 0x3000
	v_add_u32_e32 v2, s10, v239
	ds_read_b128 v[194:197], v2
	ds_read_b128 v[198:201], v2 offset:512
	ds_read_b128 v[202:205], v2 offset:2048
	ds_read_b128 v[206:209], v2 offset:2560
	ds_read_b128 v[210:213], v2 offset:4096
	ds_read_b128 v[214:217], v2 offset:4608
	ds_read_b128 v[218:221], v2 offset:6144
	ds_read_b128 v[222:225], v2 offset:6656
	s_nop 7
	v_max3_f32 v20, v114, v115, v116
	v_max3_f32 v21, v117, v118, v119
	v_max3_f32 v20, v20, v120, v121
	v_max3_f32 v21, v21, v122, v123
	v_max3_f32 v20, v20, v124, v125
	v_max3_f32 v21, v21, v126, v127
	v_max3_f32 v20, v20, v128, v129
	v_max3_f32 v21, v21, v130, v131
	v_max3_f32 v20, v20, v132, v133
	v_max3_f32 v21, v21, v134, v135
	v_max3_f32 v20, v20, v136, v137
	v_max3_f32 v21, v21, v138, v139
	v_max3_f32 v20, v20, v140, v141
	v_max3_f32 v21, v21, v142, v143
	v_max3_f32 v20, v20, v144, v145
	v_max_f32_e32 v20, v20, v21
	v_mov_b32_e32 v21, v20
	s_nop 1
	v_permlane32_swap_b32_e32 v20, v21
	v_max_f32_e32 v20, v20, v21
	v_max_f32_e32 v20, v20, v20
	v_mov_b32_e32 v242, v20
	v_xor_b32_e32 v82, 0x80000000, v20
	v_sub_f32_e32 v66, v23, v20
	v_mov_b32_e32 v83, v82
	v_mov_b32_e32 v67, v66
	v_mov_b32_e32 v84, v82
	v_mov_b32_e32 v68, v66
	v_mov_b32_e32 v85, v82
	v_mov_b32_e32 v69, v66
	v_mov_b32_e32 v86, v82
	v_mov_b32_e32 v70, v66
	v_mov_b32_e32 v87, v82
	v_mov_b32_e32 v71, v66
	v_mov_b32_e32 v88, v82
	v_mov_b32_e32 v72, v66
	v_mov_b32_e32 v89, v82
	v_mov_b32_e32 v73, v66
	v_mov_b32_e32 v90, v82
	v_mov_b32_e32 v74, v66
	v_mov_b32_e32 v91, v82
	v_mov_b32_e32 v75, v66
	v_mov_b32_e32 v92, v82
	v_mov_b32_e32 v76, v66
	v_mov_b32_e32 v93, v82
	v_mov_b32_e32 v77, v66
	v_mov_b32_e32 v94, v82
	v_mov_b32_e32 v78, v66
	v_mov_b32_e32 v95, v82
	v_mov_b32_e32 v79, v66
	v_mov_b32_e32 v96, v82
	v_mov_b32_e32 v80, v66
	v_mov_b32_e32 v97, v82
	v_mov_b32_e32 v81, v66
	v_sub_f32_e32 v114, v114, v20
	v_sub_f32_e32 v115, v115, v20
	v_sub_f32_e32 v116, v116, v20
	v_sub_f32_e32 v117, v117, v20
	v_sub_f32_e32 v118, v118, v20
	v_sub_f32_e32 v119, v119, v20
	v_sub_f32_e32 v120, v120, v20
	v_sub_f32_e32 v121, v121, v20
	v_sub_f32_e32 v122, v122, v20
	v_sub_f32_e32 v123, v123, v20
	v_sub_f32_e32 v124, v124, v20
	v_sub_f32_e32 v125, v125, v20
	v_sub_f32_e32 v126, v126, v20
	v_sub_f32_e32 v127, v127, v20
	v_sub_f32_e32 v128, v128, v20
	v_sub_f32_e32 v129, v129, v20
	v_sub_f32_e32 v130, v130, v20
	v_sub_f32_e32 v131, v131, v20
	v_sub_f32_e32 v132, v132, v20
	v_sub_f32_e32 v133, v133, v20
	v_sub_f32_e32 v134, v134, v20
	v_sub_f32_e32 v135, v135, v20
	v_sub_f32_e32 v136, v136, v20
	v_sub_f32_e32 v137, v137, v20
	v_sub_f32_e32 v138, v138, v20
	v_sub_f32_e32 v139, v139, v20
	v_sub_f32_e32 v140, v140, v20
	v_sub_f32_e32 v141, v141, v20
	v_sub_f32_e32 v142, v142, v20
	v_sub_f32_e32 v143, v143, v20
	v_sub_f32_e32 v144, v144, v20
	v_sub_f32_e32 v145, v145, v20
	s_add_i32 s79, s79, 1

.Lbd_dk_9:
	s_add_i32 s10, s79, 0
	s_and_b32 s10, s10, 3
	s_lshl_b32 s10, s10, 13
	v_add_u32_e32 v2, s10, v241
	v_mfma_f32_32x32x16_bf16 v[162:177], v[194:197], v[146:149], v[66:81]
	v_exp_f32_e32 v114, v114
	v_exp_f32_e32 v115, v115
	v_exp_f32_e32 v116, v116
	v_add_f32_e32 v22, v114, v115
	v_exp_f32_e32 v117, v117
	ds_read_b64_tr_b16 v[98:99], v2 offset:49152
	ds_read_b64_tr_b16 v[100:101], v2 offset:49664
	ds_read_b64_tr_b16 v[102:103], v2 offset:50176
	ds_read_b64_tr_b16 v[104:105], v2 offset:50688
	v_mfma_f32_32x32x16_bf16 v[178:193], v[198:201], v[146:149], v[66:81]
	v_exp_f32_e32 v118, v118
	v_add_f32_e32 v22, v22, v116
	v_exp_f32_e32 v119, v119
	v_add_f32_e32 v22, v22, v117
	v_exp_f32_e32 v120, v120
	ds_read_b64_tr_b16 v[106:107], v2 offset:51200
	ds_read_b64_tr_b16 v[108:109], v2 offset:51712
	ds_read_b64_tr_b16 v[110:111], v2 offset:52224
	ds_read_b64_tr_b16 v[112:113], v2 offset:52736
	v_mfma_f32_32x32x16_bf16 v[162:177], v[202:205], v[150:153], v[162:177]
	v_add_f32_e32 v22, v22, v118
	v_exp_f32_e32 v121, v121
	v_add_f32_e32 v22, v22, v119
	v_add_f32_e32 v22, v22, v120
	v_add_f32_e32 v22, v22, v121
	ds_read_b64_tr_b16 v[4:5], v2 offset:53248
	ds_read_b64_tr_b16 v[6:7], v2 offset:53760
	ds_read_b64_tr_b16 v[8:9], v2 offset:54272
	ds_read_b64_tr_b16 v[10:11], v2 offset:54784
	v_mfma_f32_32x32x16_bf16 v[178:193], v[206:209], v[150:153], v[178:193]
	v_cvt_pk_bf16_f32 v114, v114, v115
	v_cvt_pk_bf16_f32 v115, v116, v117
	v_cvt_pk_bf16_f32 v116, v118, v119
	v_cvt_pk_bf16_f32 v117, v120, v121
	ds_read_b64_tr_b16 v[12:13], v2 offset:55296
	ds_read_b64_tr_b16 v[14:15], v2 offset:55808
	ds_read_b64_tr_b16 v[16:17], v2 offset:56320
	ds_read_b64_tr_b16 v[18:19], v2 offset:56832
	v_mfma_f32_32x32x16_bf16 v[162:177], v[210:213], v[154:157], v[162:177]
	v_exp_f32_e32 v122, v122
	v_exp_f32_e32 v123, v123
	v_exp_f32_e32 v124, v124
	v_add_f32_e32 v22, v22, v122
	v_exp_f32_e32 v125, v125
	v_mfma_f32_32x32x16_bf16 v[178:193], v[214:217], v[154:157], v[178:193]
	v_add_f32_e32 v22, v22, v123
	v_exp_f32_e32 v126, v126
	v_add_f32_e32 v22, v22, v124
	v_exp_f32_e32 v127, v127
	v_add_f32_e32 v22, v22, v125
	v_mfma_f32_32x32x16_bf16 v[162:177], v[218:221], v[158:161], v[162:177]
	v_exp_f32_e32 v128, v128
	v_add_f32_e32 v22, v22, v126
	v_exp_f32_e32 v129, v129
	v_add_f32_e32 v22, v22, v127
	v_add_f32_e32 v22, v22, v128
	v_mfma_f32_32x32x16_bf16 v[178:193], v[222:225], v[158:161], v[178:193]
	v_add_f32_e32 v22, v22, v129
	v_cvt_pk_bf16_f32 v122, v122, v123
	v_cvt_pk_bf16_f32 v123, v124, v125
	v_cvt_pk_bf16_f32 v124, v126, v127
	v_cvt_pk_bf16_f32 v125, v128, v129
	s_waitcnt lgkmcnt(0)
	s_add_i32 s10, s79, 2
	s_and_b32 s10, s10, 3
	s_mulk_i32 s10, 0x3000
	v_add_u32_e32 v2, s10, v239
	v_mfma_f32_32x32x16_bf16 v[50:65], v[114:117], v[98:101], v[50:65]
	v_exp_f32_e32 v130, v130
	v_exp_f32_e32 v131, v131
	v_exp_f32_e32 v132, v132
	v_add_f32_e32 v22, v22, v130
	v_exp_f32_e32 v133, v133
	v_add_f32_e32 v22, v22, v131
	v_exp_f32_e32 v134, v134
	v_add_f32_e32 v22, v22, v132
	v_exp_f32_e32 v135, v135
	v_add_f32_e32 v22, v22, v133
	ds_read_b128 v[194:197], v2
	ds_read_b128 v[198:201], v2 offset:512
	v_mfma_f32_32x32x16_bf16 v[34:49], v[114:117], v[4:7], v[34:49]
	v_exp_f32_e32 v136, v136
	v_add_f32_e32 v22, v22, v134
	v_exp_f32_e32 v137, v137
	v_add_f32_e32 v22, v22, v135
	v_add_f32_e32 v22, v22, v136
	v_add_f32_e32 v22, v22, v137
	v_cvt_pk_bf16_f32 v130, v130, v131
	v_cvt_pk_bf16_f32 v131, v132, v133
	v_cvt_pk_bf16_f32 v132, v134, v135
	v_cvt_pk_bf16_f32 v133, v136, v137
	ds_read_b128 v[202:205], v2 offset:2048
	ds_read_b128 v[206:209], v2 offset:2560
	v_mfma_f32_32x32x16_bf16 v[50:65], v[122:125], v[102:105], v[50:65]
	v_exp_f32_e32 v138, v138
	v_exp_f32_e32 v139, v139
	v_exp_f32_e32 v140, v140
	v_add_f32_e32 v22, v22, v138
	v_exp_f32_e32 v141, v141
	v_add_f32_e32 v22, v22, v139
	v_exp_f32_e32 v142, v142
	v_add_f32_e32 v22, v22, v140
	v_exp_f32_e32 v143, v143
	v_add_f32_e32 v22, v22, v141
	ds_read_b128 v[210:213], v2 offset:4096
	ds_read_b128 v[214:217], v2 offset:4608
	v_mfma_f32_32x32x16_bf16 v[34:49], v[122:125], v[8:11], v[34:49]
	v_exp_f32_e32 v144, v144
	v_add_f32_e32 v22, v22, v142
	v_exp_f32_e32 v145, v145
	v_add_f32_e32 v22, v22, v143
	v_add_f32_e32 v22, v22, v144
	v_add_f32_e32 v22, v22, v145
	v_cvt_pk_bf16_f32 v138, v138, v139
	v_cvt_pk_bf16_f32 v139, v140, v141
	v_cvt_pk_bf16_f32 v140, v142, v143
	v_cvt_pk_bf16_f32 v141, v144, v145
	v_add_f32_e32 v240, v240, v22
	ds_read_b128 v[218:221], v2 offset:6144
	ds_read_b128 v[222:225], v2 offset:6656
	v_mfma_f32_32x32x16_bf16 v[50:65], v[130:133], v[106:109], v[50:65]
	v_max3_f32 v20, v162, v163, v164
	v_max3_f32 v21, v165, v166, v167
	v_max3_f32 v20, v20, v168, v169
	v_max3_f32 v21, v21, v170, v171
	v_max3_f32 v20, v20, v172, v173
	v_mfma_f32_32x32x16_bf16 v[34:49], v[130:133], v[12:15], v[34:49]
	v_max3_f32 v21, v21, v174, v175
	v_max3_f32 v20, v20, v176, v177
	v_max3_f32 v21, v21, v178, v179
	v_max3_f32 v20, v20, v180, v181
	v_max3_f32 v21, v21, v182, v183
	v_mfma_f32_32x32x16_bf16 v[50:65], v[138:141], v[110:113], v[50:65]
	v_max3_f32 v20, v20, v184, v185
	v_max3_f32 v21, v21, v186, v187
	v_max3_f32 v20, v20, v188, v189
	v_max3_f32 v21, v21, v190, v191
	v_mfma_f32_32x32x16_bf16 v[34:49], v[138:141], v[16:19], v[34:49]
	v_max3_f32 v20, v20, v192, v193
	v_max_f32_e32 v20, v20, v21
	v_cmp_lt_f32_e32 vcc, s41, v20
	s_cbranch_vccz .Lbd_nors_10
	s_nop 15
	s_nop 15
	v_mov_b32_e32 v21, v20
	s_nop 1
	v_permlane32_swap_b32_e32 v20, v21
	v_max_f32_e32 v20, v20, v21
	v_max_f32_e32 v20, v20, v20
	v_max_f32_e32 v122, 0, v20
	v_exp_f32_e64 v123, -v122
	v_add_f32_e32 v242, v242, v122
	v_xor_b32_e32 v82, 0x80000000, v242
	v_sub_f32_e32 v66, v23, v242
	v_mov_b32_e32 v83, v82
	v_mov_b32_e32 v67, v66
	v_mov_b32_e32 v84, v82
	v_mov_b32_e32 v68, v66
	v_mov_b32_e32 v85, v82
	v_mov_b32_e32 v69, v66
	v_mov_b32_e32 v86, v82
	v_mov_b32_e32 v70, v66
	v_mov_b32_e32 v87, v82
	v_mov_b32_e32 v71, v66
	v_mov_b32_e32 v88, v82
	v_mov_b32_e32 v72, v66
	v_mov_b32_e32 v89, v82
	v_mov_b32_e32 v73, v66
	v_mov_b32_e32 v90, v82
	v_mov_b32_e32 v74, v66
	v_mov_b32_e32 v91, v82
	v_mov_b32_e32 v75, v66
	v_mov_b32_e32 v92, v82
	v_mov_b32_e32 v76, v66
	v_mov_b32_e32 v93, v82
	v_mov_b32_e32 v77, v66
	v_mov_b32_e32 v94, v82
	v_mov_b32_e32 v78, v66
	v_mov_b32_e32 v95, v82
	v_mov_b32_e32 v79, v66
	v_mov_b32_e32 v96, v82
	v_mov_b32_e32 v80, v66
	v_mov_b32_e32 v97, v82
	v_mov_b32_e32 v81, v66
	v_sub_f32_e32 v162, v162, v122
	v_sub_f32_e32 v163, v163, v122
	v_sub_f32_e32 v164, v164, v122
	v_sub_f32_e32 v165, v165, v122
	v_sub_f32_e32 v166, v166, v122
	v_sub_f32_e32 v167, v167, v122
	v_sub_f32_e32 v168, v168, v122
	v_sub_f32_e32 v169, v169, v122
	v_sub_f32_e32 v170, v170, v122
	v_sub_f32_e32 v171, v171, v122
	v_sub_f32_e32 v172, v172, v122
	v_sub_f32_e32 v173, v173, v122
	v_sub_f32_e32 v174, v174, v122
	v_sub_f32_e32 v175, v175, v122
	v_sub_f32_e32 v176, v176, v122
	v_sub_f32_e32 v177, v177, v122
	v_sub_f32_e32 v178, v178, v122
	v_sub_f32_e32 v179, v179, v122
	v_sub_f32_e32 v180, v180, v122
	v_sub_f32_e32 v181, v181, v122
	v_sub_f32_e32 v182, v182, v122
	v_sub_f32_e32 v183, v183, v122
	v_sub_f32_e32 v184, v184, v122
	v_sub_f32_e32 v185, v185, v122
	v_sub_f32_e32 v186, v186, v122
	v_sub_f32_e32 v187, v187, v122
	v_sub_f32_e32 v188, v188, v122
	v_sub_f32_e32 v189, v189, v122
	v_sub_f32_e32 v190, v190, v122
	v_sub_f32_e32 v191, v191, v122
	v_sub_f32_e32 v192, v192, v122
	v_sub_f32_e32 v193, v193, v122
	v_mul_f32_e32 v240, v240, v123
	v_cmp_gt_u32_e32 vcc, 32, v233
	s_and_saveexec_b64 s[12:13], vcc
	ds_write_b32 v244, v123
	s_mov_b64 exec, s[12:13]
	ds_read_b128 v[126:129], v237 offset:0
	s_waitcnt lgkmcnt(0)
	v_mul_f32_e32 v50, v50, v126
	v_mul_f32_e32 v34, v34, v126
	v_mul_f32_e32 v51, v51, v127
	v_mul_f32_e32 v35, v35, v127
	v_mul_f32_e32 v52, v52, v128
	v_mul_f32_e32 v36, v36, v128
	v_mul_f32_e32 v53, v53, v129
	v_mul_f32_e32 v37, v37, v129
	ds_read_b128 v[126:129], v237 offset:32
	s_waitcnt lgkmcnt(0)
	v_mul_f32_e32 v54, v54, v126
	v_mul_f32_e32 v38, v38, v126
	v_mul_f32_e32 v55, v55, v127
	v_mul_f32_e32 v39, v39, v127
	v_mul_f32_e32 v56, v56, v128
	v_mul_f32_e32 v40, v40, v128
	v_mul_f32_e32 v57, v57, v129
	v_mul_f32_e32 v41, v41, v129
	ds_read_b128 v[126:129], v237 offset:64
	s_waitcnt lgkmcnt(0)
	v_mul_f32_e32 v58, v58, v126
	v_mul_f32_e32 v42, v42, v126
	v_mul_f32_e32 v59, v59, v127
	v_mul_f32_e32 v43, v43, v127
	v_mul_f32_e32 v60, v60, v128
	v_mul_f32_e32 v44, v44, v128
	v_mul_f32_e32 v61, v61, v129
	v_mul_f32_e32 v45, v45, v129
	ds_read_b128 v[126:129], v237 offset:96
	s_waitcnt lgkmcnt(0)
	v_mul_f32_e32 v62, v62, v126
	v_mul_f32_e32 v46, v46, v126
	v_mul_f32_e32 v63, v63, v127
	v_mul_f32_e32 v47, v47, v127
	v_mul_f32_e32 v64, v64, v128
	v_mul_f32_e32 v48, v48, v128
	v_mul_f32_e32 v65, v65, v129
	v_mul_f32_e32 v49, v49, v129
.Lbd_nors_10:
	s_add_i32 s79, s79, 1
	s_waitcnt vmcnt(2)
	s_cmp_lt_u32 s79, 9
	s_cbranch_scc1 .Lbd_w_11
	s_waitcnt vmcnt(0)

.Lbd_dk_13:
	s_add_i32 s10, s79, 0
	s_and_b32 s10, s10, 3
	s_lshl_b32 s10, s10, 13
	v_add_u32_e32 v2, s10, v241
	v_mfma_f32_32x32x16_bf16 v[114:129], v[194:197], v[146:149], v[66:81]
	v_exp_f32_e32 v162, v162
	v_exp_f32_e32 v163, v163
	v_exp_f32_e32 v164, v164
	v_add_f32_e32 v22, v162, v163
	v_exp_f32_e32 v165, v165
	ds_read_b64_tr_b16 v[98:99], v2 offset:49152
	ds_read_b64_tr_b16 v[100:101], v2 offset:49664
	ds_read_b64_tr_b16 v[102:103], v2 offset:50176
	ds_read_b64_tr_b16 v[104:105], v2 offset:50688
	v_mfma_f32_32x32x16_bf16 v[130:145], v[198:201], v[146:149], v[66:81]
	v_exp_f32_e32 v166, v166
	v_add_f32_e32 v22, v22, v164
	v_exp_f32_e32 v167, v167
	v_add_f32_e32 v22, v22, v165
	v_exp_f32_e32 v168, v168
	ds_read_b64_tr_b16 v[106:107], v2 offset:51200
	ds_read_b64_tr_b16 v[108:109], v2 offset:51712
	ds_read_b64_tr_b16 v[110:111], v2 offset:52224
	ds_read_b64_tr_b16 v[112:113], v2 offset:52736
	v_mfma_f32_32x32x16_bf16 v[114:129], v[202:205], v[150:153], v[114:129]
	v_add_f32_e32 v22, v22, v166
	v_exp_f32_e32 v169, v169
	v_add_f32_e32 v22, v22, v167
	v_add_f32_e32 v22, v22, v168
	v_add_f32_e32 v22, v22, v169
	ds_read_b64_tr_b16 v[4:5], v2 offset:53248
	ds_read_b64_tr_b16 v[6:7], v2 offset:53760
	ds_read_b64_tr_b16 v[8:9], v2 offset:54272
	ds_read_b64_tr_b16 v[10:11], v2 offset:54784
	v_mfma_f32_32x32x16_bf16 v[130:145], v[206:209], v[150:153], v[130:145]
	v_cvt_pk_bf16_f32 v162, v162, v163
	v_cvt_pk_bf16_f32 v163, v164, v165
	v_cvt_pk_bf16_f32 v164, v166, v167
	v_cvt_pk_bf16_f32 v165, v168, v169
	ds_read_b64_tr_b16 v[12:13], v2 offset:55296
	ds_read_b64_tr_b16 v[14:15], v2 offset:55808
	ds_read_b64_tr_b16 v[16:17], v2 offset:56320
	ds_read_b64_tr_b16 v[18:19], v2 offset:56832
	v_mfma_f32_32x32x16_bf16 v[114:129], v[210:213], v[154:157], v[114:129]
	v_exp_f32_e32 v170, v170
	v_exp_f32_e32 v171, v171
	v_exp_f32_e32 v172, v172
	v_add_f32_e32 v22, v22, v170
	v_exp_f32_e32 v173, v173
	v_mfma_f32_32x32x16_bf16 v[130:145], v[214:217], v[154:157], v[130:145]
	v_add_f32_e32 v22, v22, v171
	v_exp_f32_e32 v174, v174
	v_add_f32_e32 v22, v22, v172
	v_exp_f32_e32 v175, v175
	v_add_f32_e32 v22, v22, v173
	v_mfma_f32_32x32x16_bf16 v[114:129], v[218:221], v[158:161], v[114:129]
	v_exp_f32_e32 v176, v176
	v_add_f32_e32 v22, v22, v174
	v_exp_f32_e32 v177, v177
	v_add_f32_e32 v22, v22, v175
	v_add_f32_e32 v22, v22, v176
	v_mfma_f32_32x32x16_bf16 v[130:145], v[222:225], v[158:161], v[130:145]
	v_add_f32_e32 v22, v22, v177
	v_cvt_pk_bf16_f32 v170, v170, v171
	v_cvt_pk_bf16_f32 v171, v172, v173
	v_cvt_pk_bf16_f32 v172, v174, v175
	v_cvt_pk_bf16_f32 v173, v176, v177
	s_waitcnt lgkmcnt(0)
	s_add_i32 s10, s79, 2
	s_and_b32 s10, s10, 3
	s_mulk_i32 s10, 0x3000
	v_add_u32_e32 v2, s10, v239
	v_mfma_f32_32x32x16_bf16 v[50:65], v[162:165], v[98:101], v[50:65]
	v_exp_f32_e32 v178, v178
	v_exp_f32_e32 v179, v179
	v_exp_f32_e32 v180, v180
	v_add_f32_e32 v22, v22, v178
	v_exp_f32_e32 v181, v181
	v_add_f32_e32 v22, v22, v179
	v_exp_f32_e32 v182, v182
	v_add_f32_e32 v22, v22, v180
	v_exp_f32_e32 v183, v183
	v_add_f32_e32 v22, v22, v181
	ds_read_b128 v[194:197], v2
	ds_read_b128 v[198:201], v2 offset:512
	v_mfma_f32_32x32x16_bf16 v[34:49], v[162:165], v[4:7], v[34:49]
	v_exp_f32_e32 v184, v184
	v_add_f32_e32 v22, v22, v182
	v_exp_f32_e32 v185, v185
	v_add_f32_e32 v22, v22, v183
	v_add_f32_e32 v22, v22, v184
	v_add_f32_e32 v22, v22, v185
	v_cvt_pk_bf16_f32 v178, v178, v179
	v_cvt_pk_bf16_f32 v179, v180, v181
	v_cvt_pk_bf16_f32 v180, v182, v183
	v_cvt_pk_bf16_f32 v181, v184, v185
	ds_read_b128 v[202:205], v2 offset:2048
	ds_read_b128 v[206:209], v2 offset:2560
	v_mfma_f32_32x32x16_bf16 v[50:65], v[170:173], v[102:105], v[50:65]
	v_exp_f32_e32 v186, v186
	v_exp_f32_e32 v187, v187
	v_exp_f32_e32 v188, v188
	v_add_f32_e32 v22, v22, v186
	v_exp_f32_e32 v189, v189
	v_add_f32_e32 v22, v22, v187
	v_exp_f32_e32 v190, v190
	v_add_f32_e32 v22, v22, v188
	v_exp_f32_e32 v191, v191
	v_add_f32_e32 v22, v22, v189
	ds_read_b128 v[210:213], v2 offset:4096
	ds_read_b128 v[214:217], v2 offset:4608
	v_mfma_f32_32x32x16_bf16 v[34:49], v[170:173], v[8:11], v[34:49]
	v_exp_f32_e32 v192, v192
	v_add_f32_e32 v22, v22, v190
	v_exp_f32_e32 v193, v193
	v_add_f32_e32 v22, v22, v191
	v_add_f32_e32 v22, v22, v192
	v_add_f32_e32 v22, v22, v193
	v_cvt_pk_bf16_f32 v186, v186, v187
	v_cvt_pk_bf16_f32 v187, v188, v189
	v_cvt_pk_bf16_f32 v188, v190, v191
	v_cvt_pk_bf16_f32 v189, v192, v193
	v_add_f32_e32 v240, v240, v22
	ds_read_b128 v[218:221], v2 offset:6144
	ds_read_b128 v[222:225], v2 offset:6656
	v_mfma_f32_32x32x16_bf16 v[50:65], v[178:181], v[106:109], v[50:65]
	v_max3_f32 v20, v114, v115, v116
	v_max3_f32 v21, v117, v118, v119
	v_max3_f32 v20, v20, v120, v121
	v_max3_f32 v21, v21, v122, v123
	v_max3_f32 v20, v20, v124, v125
	v_mfma_f32_32x32x16_bf16 v[34:49], v[178:181], v[12:15], v[34:49]
	v_max3_f32 v21, v21, v126, v127
	v_max3_f32 v20, v20, v128, v129
	v_max3_f32 v21, v21, v130, v131
	v_max3_f32 v20, v20, v132, v133
	v_max3_f32 v21, v21, v134, v135
	v_mfma_f32_32x32x16_bf16 v[50:65], v[186:189], v[110:113], v[50:65]
	v_max3_f32 v20, v20, v136, v137
	v_max3_f32 v21, v21, v138, v139
	v_max3_f32 v20, v20, v140, v141
	v_max3_f32 v21, v21, v142, v143
	v_mfma_f32_32x32x16_bf16 v[34:49], v[186:189], v[16:19], v[34:49]
	v_max3_f32 v20, v20, v144, v145
	v_max_f32_e32 v20, v20, v21
	v_cmp_lt_f32_e32 vcc, s41, v20
	s_cbranch_vccz .Lbd_nors_14
	s_nop 15
	s_nop 15
	v_mov_b32_e32 v21, v20
	s_nop 1
	v_permlane32_swap_b32_e32 v20, v21
	v_max_f32_e32 v20, v20, v21
	v_max_f32_e32 v20, v20, v20
	v_max_f32_e32 v170, 0, v20
	v_exp_f32_e64 v171, -v170
	v_add_f32_e32 v242, v242, v170
	v_xor_b32_e32 v82, 0x80000000, v242
	v_sub_f32_e32 v66, v23, v242
	v_mov_b32_e32 v83, v82
	v_mov_b32_e32 v67, v66
	v_mov_b32_e32 v84, v82
	v_mov_b32_e32 v68, v66
	v_mov_b32_e32 v85, v82
	v_mov_b32_e32 v69, v66
	v_mov_b32_e32 v86, v82
	v_mov_b32_e32 v70, v66
	v_mov_b32_e32 v87, v82
	v_mov_b32_e32 v71, v66
	v_mov_b32_e32 v88, v82
	v_mov_b32_e32 v72, v66
	v_mov_b32_e32 v89, v82
	v_mov_b32_e32 v73, v66
	v_mov_b32_e32 v90, v82
	v_mov_b32_e32 v74, v66
	v_mov_b32_e32 v91, v82
	v_mov_b32_e32 v75, v66
	v_mov_b32_e32 v92, v82
	v_mov_b32_e32 v76, v66
	v_mov_b32_e32 v93, v82
	v_mov_b32_e32 v77, v66
	v_mov_b32_e32 v94, v82
	v_mov_b32_e32 v78, v66
	v_mov_b32_e32 v95, v82
	v_mov_b32_e32 v79, v66
	v_mov_b32_e32 v96, v82
	v_mov_b32_e32 v80, v66
	v_mov_b32_e32 v97, v82
	v_mov_b32_e32 v81, v66
	v_sub_f32_e32 v114, v114, v170
	v_sub_f32_e32 v115, v115, v170
	v_sub_f32_e32 v116, v116, v170
	v_sub_f32_e32 v117, v117, v170
	v_sub_f32_e32 v118, v118, v170
	v_sub_f32_e32 v119, v119, v170
	v_sub_f32_e32 v120, v120, v170
	v_sub_f32_e32 v121, v121, v170
	v_sub_f32_e32 v122, v122, v170
	v_sub_f32_e32 v123, v123, v170
	v_sub_f32_e32 v124, v124, v170
	v_sub_f32_e32 v125, v125, v170
	v_sub_f32_e32 v126, v126, v170
	v_sub_f32_e32 v127, v127, v170
	v_sub_f32_e32 v128, v128, v170
	v_sub_f32_e32 v129, v129, v170
	v_sub_f32_e32 v130, v130, v170
	v_sub_f32_e32 v131, v131, v170
	v_sub_f32_e32 v132, v132, v170
	v_sub_f32_e32 v133, v133, v170
	v_sub_f32_e32 v134, v134, v170
	v_sub_f32_e32 v135, v135, v170
	v_sub_f32_e32 v136, v136, v170
	v_sub_f32_e32 v137, v137, v170
	v_sub_f32_e32 v138, v138, v170
	v_sub_f32_e32 v139, v139, v170
	v_sub_f32_e32 v140, v140, v170
	v_sub_f32_e32 v141, v141, v170
	v_sub_f32_e32 v142, v142, v170
	v_sub_f32_e32 v143, v143, v170
	v_sub_f32_e32 v144, v144, v170
	v_sub_f32_e32 v145, v145, v170
	v_mul_f32_e32 v240, v240, v171
	v_cmp_gt_u32_e32 vcc, 32, v233
	s_and_saveexec_b64 s[12:13], vcc
	ds_write_b32 v244, v171
	s_mov_b64 exec, s[12:13]
	ds_read_b128 v[174:177], v237 offset:0
	s_waitcnt lgkmcnt(0)
	v_mul_f32_e32 v50, v50, v174
	v_mul_f32_e32 v34, v34, v174
	v_mul_f32_e32 v51, v51, v175
	v_mul_f32_e32 v35, v35, v175
	v_mul_f32_e32 v52, v52, v176
	v_mul_f32_e32 v36, v36, v176
	v_mul_f32_e32 v53, v53, v177
	v_mul_f32_e32 v37, v37, v177
	ds_read_b128 v[174:177], v237 offset:32
	s_waitcnt lgkmcnt(0)
	v_mul_f32_e32 v54, v54, v174
	v_mul_f32_e32 v38, v38, v174
	v_mul_f32_e32 v55, v55, v175
	v_mul_f32_e32 v39, v39, v175
	v_mul_f32_e32 v56, v56, v176
	v_mul_f32_e32 v40, v40, v176
	v_mul_f32_e32 v57, v57, v177
	v_mul_f32_e32 v41, v41, v177
	ds_read_b128 v[174:177], v237 offset:64
	s_waitcnt lgkmcnt(0)
	v_mul_f32_e32 v58, v58, v174
	v_mul_f32_e32 v42, v42, v174
	v_mul_f32_e32 v59, v59, v175
	v_mul_f32_e32 v43, v43, v175
	v_mul_f32_e32 v60, v60, v176
	v_mul_f32_e32 v44, v44, v176
	v_mul_f32_e32 v61, v61, v177
	v_mul_f32_e32 v45, v45, v177
	ds_read_b128 v[174:177], v237 offset:96
	s_waitcnt lgkmcnt(0)
	v_mul_f32_e32 v62, v62, v174
	v_mul_f32_e32 v46, v46, v174
	v_mul_f32_e32 v63, v63, v175
	v_mul_f32_e32 v47, v47, v175
	v_mul_f32_e32 v64, v64, v176
	v_mul_f32_e32 v48, v48, v176
	v_mul_f32_e32 v65, v65, v177
	v_mul_f32_e32 v49, v49, v177

.Lbd_dk_29:
	s_add_i32 s10, s79, 0
	s_and_b32 s10, s10, 3
	s_lshl_b32 s10, s10, 13
	v_add_u32_e32 v2, s10, v241
	v_mfma_f32_32x32x16_bf16 v[114:129], v[194:197], v[146:149], v[82:97]
	v_exp_f32_e32 v162, v162
	v_exp_f32_e32 v163, v163
	v_exp_f32_e32 v164, v164
	v_add_f32_e32 v22, v162, v163
	v_exp_f32_e32 v165, v165
	ds_read_b64_tr_b16 v[98:99], v2 offset:49152
	ds_read_b64_tr_b16 v[100:101], v2 offset:49664
	ds_read_b64_tr_b16 v[102:103], v2 offset:50176
	ds_read_b64_tr_b16 v[104:105], v2 offset:50688
	v_mfma_f32_32x32x16_bf16 v[130:145], v[198:201], v[146:149], v[82:97]
	v_exp_f32_e32 v166, v166
	v_add_f32_e32 v22, v22, v164
	v_exp_f32_e32 v167, v167
	v_add_f32_e32 v22, v22, v165
	v_exp_f32_e32 v168, v168
	ds_read_b64_tr_b16 v[106:107], v2 offset:51200
	ds_read_b64_tr_b16 v[108:109], v2 offset:51712
	ds_read_b64_tr_b16 v[110:111], v2 offset:52224
	ds_read_b64_tr_b16 v[112:113], v2 offset:52736
	v_mfma_f32_32x32x16_bf16 v[114:129], v[202:205], v[150:153], v[114:129]
	v_add_f32_e32 v22, v22, v166
	v_exp_f32_e32 v169, v169
	v_add_f32_e32 v22, v22, v167
	v_add_f32_e32 v22, v22, v168
	v_add_f32_e32 v22, v22, v169
	ds_read_b64_tr_b16 v[4:5], v2 offset:53248
	ds_read_b64_tr_b16 v[6:7], v2 offset:53760
	ds_read_b64_tr_b16 v[8:9], v2 offset:54272
	ds_read_b64_tr_b16 v[10:11], v2 offset:54784
	v_mfma_f32_32x32x16_bf16 v[130:145], v[206:209], v[150:153], v[130:145]
	v_cvt_pk_bf16_f32 v162, v162, v163
	v_cvt_pk_bf16_f32 v163, v164, v165
	v_cvt_pk_bf16_f32 v164, v166, v167
	v_cvt_pk_bf16_f32 v165, v168, v169
	ds_read_b64_tr_b16 v[12:13], v2 offset:55296
	ds_read_b64_tr_b16 v[14:15], v2 offset:55808
	ds_read_b64_tr_b16 v[16:17], v2 offset:56320
	ds_read_b64_tr_b16 v[18:19], v2 offset:56832
	v_mfma_f32_32x32x16_bf16 v[114:129], v[210:213], v[154:157], v[114:129]
	v_exp_f32_e32 v170, v170
	v_exp_f32_e32 v171, v171
	v_exp_f32_e32 v172, v172
	v_add_f32_e32 v22, v22, v170
	v_exp_f32_e32 v173, v173
	v_mfma_f32_32x32x16_bf16 v[130:145], v[214:217], v[154:157], v[130:145]
	v_add_f32_e32 v22, v22, v171
	v_exp_f32_e32 v174, v174
	v_add_f32_e32 v22, v22, v172
	v_exp_f32_e32 v175, v175
	v_add_f32_e32 v22, v22, v173
	v_mfma_f32_32x32x16_bf16 v[114:129], v[218:221], v[158:161], v[114:129]
	v_exp_f32_e32 v176, v176
	v_add_f32_e32 v22, v22, v174
	v_exp_f32_e32 v177, v177
	v_add_f32_e32 v22, v22, v175
	v_add_f32_e32 v22, v22, v176
	v_mfma_f32_32x32x16_bf16 v[130:145], v[222:225], v[158:161], v[130:145]
	v_add_f32_e32 v22, v22, v177
	v_cvt_pk_bf16_f32 v170, v170, v171
	v_cvt_pk_bf16_f32 v171, v172, v173
	v_cvt_pk_bf16_f32 v172, v174, v175
	v_cvt_pk_bf16_f32 v173, v176, v177
	s_waitcnt lgkmcnt(0)
	s_add_i32 s10, s79, 2
	s_and_b32 s10, s10, 3
	s_mulk_i32 s10, 0x3000
	v_add_u32_e32 v2, s10, v239
	v_mfma_f32_32x32x16_bf16 v[50:65], v[162:165], v[98:101], v[50:65]
	v_exp_f32_e32 v178, v178
	v_exp_f32_e32 v179, v179
	v_exp_f32_e32 v180, v180
	v_add_f32_e32 v22, v22, v178
	v_exp_f32_e32 v181, v181
	v_add_f32_e32 v22, v22, v179
	v_exp_f32_e32 v182, v182
	v_add_f32_e32 v22, v22, v180
	v_exp_f32_e32 v183, v183
	v_add_f32_e32 v22, v22, v181
	ds_read_b128 v[194:197], v2
	ds_read_b128 v[198:201], v2 offset:512
	v_mfma_f32_32x32x16_bf16 v[34:49], v[162:165], v[4:7], v[34:49]
	v_exp_f32_e32 v184, v184
	v_add_f32_e32 v22, v22, v182
	v_exp_f32_e32 v185, v185
	v_add_f32_e32 v22, v22, v183
	v_add_f32_e32 v22, v22, v184
	v_add_f32_e32 v22, v22, v185
	v_cvt_pk_bf16_f32 v178, v178, v179
	v_cvt_pk_bf16_f32 v179, v180, v181
	v_cvt_pk_bf16_f32 v180, v182, v183
	v_cvt_pk_bf16_f32 v181, v184, v185
	ds_read_b128 v[202:205], v2 offset:2048
	ds_read_b128 v[206:209], v2 offset:2560
	v_mfma_f32_32x32x16_bf16 v[50:65], v[170:173], v[102:105], v[50:65]
	v_exp_f32_e32 v186, v186
	v_exp_f32_e32 v187, v187
	v_exp_f32_e32 v188, v188
	v_add_f32_e32 v22, v22, v186
	v_exp_f32_e32 v189, v189
	v_add_f32_e32 v22, v22, v187
	v_exp_f32_e32 v190, v190
	v_add_f32_e32 v22, v22, v188
	v_exp_f32_e32 v191, v191
	v_add_f32_e32 v22, v22, v189
	ds_read_b128 v[210:213], v2 offset:4096
	ds_read_b128 v[214:217], v2 offset:4608
	v_mfma_f32_32x32x16_bf16 v[34:49], v[170:173], v[8:11], v[34:49]
	v_exp_f32_e32 v192, v192
	v_add_f32_e32 v22, v22, v190
	v_exp_f32_e32 v193, v193
	v_add_f32_e32 v22, v22, v191
	v_add_f32_e32 v22, v22, v192
	v_add_f32_e32 v22, v22, v193
	v_cvt_pk_bf16_f32 v186, v186, v187
	v_cvt_pk_bf16_f32 v187, v188, v189
	v_cvt_pk_bf16_f32 v188, v190, v191
	v_cvt_pk_bf16_f32 v189, v192, v193
	v_add_f32_e32 v240, v240, v22
	ds_read_b128 v[218:221], v2 offset:6144
	ds_read_b128 v[222:225], v2 offset:6656
	v_mfma_f32_32x32x16_bf16 v[50:65], v[178:181], v[106:109], v[50:65]
	v_mfma_f32_32x32x16_bf16 v[34:49], v[178:181], v[12:15], v[34:49]
	v_mfma_f32_32x32x16_bf16 v[50:65], v[186:189], v[110:113], v[50:65]
	v_mfma_f32_32x32x16_bf16 v[34:49], v[186:189], v[16:19], v[34:49]
	ds_read2_b32 v[30:31], v29 offset0:187 offset1:186
	ds_read2_b32 v[32:33], v29 offset0:185 offset1:184
	ds_read2_b32 v[246:247], v29 offset0:179 offset1:178
	ds_read2_b32 v[248:249], v29 offset0:177 offset1:176
	s_waitcnt lgkmcnt(0)
	v_add_f32_e32 v114, v114, v30
	v_add_f32_e32 v115, v115, v31
	v_add_f32_e32 v116, v116, v32
	v_add_f32_e32 v117, v117, v33
	v_add_f32_e32 v118, v118, v246
	v_add_f32_e32 v119, v119, v247
	v_add_f32_e32 v120, v120, v248
	v_add_f32_e32 v121, v121, v249
	ds_read2_b32 v[30:31], v29 offset0:171 offset1:170
	ds_read2_b32 v[32:33], v29 offset0:169 offset1:168
	ds_read2_b32 v[246:247], v29 offset0:163 offset1:162
	ds_read2_b32 v[248:249], v29 offset0:161 offset1:160
	s_waitcnt lgkmcnt(0)
	v_add_f32_e32 v122, v122, v30
	v_add_f32_e32 v123, v123, v31
	v_add_f32_e32 v124, v124, v32
	v_add_f32_e32 v125, v125, v33
	v_add_f32_e32 v126, v126, v246
	v_add_f32_e32 v127, v127, v247
	v_add_f32_e32 v128, v128, v248
	v_add_f32_e32 v129, v129, v249
	ds_read2_b32 v[30:31], v29 offset0:155 offset1:154
	ds_read2_b32 v[32:33], v29 offset0:153 offset1:152
	ds_read2_b32 v[246:247], v29 offset0:147 offset1:146
	ds_read2_b32 v[248:249], v29 offset0:145 offset1:144
	s_waitcnt lgkmcnt(0)
	v_add_f32_e32 v130, v130, v30
	v_add_f32_e32 v131, v131, v31
	v_add_f32_e32 v132, v132, v32
	v_add_f32_e32 v133, v133, v33
	v_add_f32_e32 v134, v134, v246
	v_add_f32_e32 v135, v135, v247
	v_add_f32_e32 v136, v136, v248
	v_add_f32_e32 v137, v137, v249
	ds_read2_b32 v[30:31], v29 offset0:139 offset1:138
	ds_read2_b32 v[32:33], v29 offset0:137 offset1:136
	ds_read2_b32 v[246:247], v29 offset0:131 offset1:130
	ds_read2_b32 v[248:249], v29 offset0:129 offset1:128
	s_waitcnt lgkmcnt(0)
	v_add_f32_e32 v138, v138, v30
	v_add_f32_e32 v139, v139, v31
	v_add_f32_e32 v140, v140, v32
	v_add_f32_e32 v141, v141, v33
	v_add_f32_e32 v142, v142, v246
	v_add_f32_e32 v143, v143, v247
	v_add_f32_e32 v144, v144, v248
	v_add_f32_e32 v145, v145, v249
	v_max3_f32 v20, v114, v115, v116
	v_max3_f32 v21, v117, v118, v119
	v_max3_f32 v20, v20, v120, v121
	v_max3_f32 v21, v21, v122, v123
	v_max3_f32 v20, v20, v124, v125
	v_max3_f32 v21, v21, v126, v127
	v_max3_f32 v20, v20, v128, v129
	v_max3_f32 v21, v21, v130, v131
	v_max3_f32 v20, v20, v132, v133
	v_max3_f32 v21, v21, v134, v135
	v_max3_f32 v20, v20, v136, v137
	v_max3_f32 v21, v21, v138, v139
	v_max3_f32 v20, v20, v140, v141
	v_max3_f32 v21, v21, v142, v143
	v_max3_f32 v20, v20, v144, v145
	v_max_f32_e32 v20, v20, v21
	v_cmp_lt_f32_e32 vcc, s41, v20
	s_cbranch_vccz .Lbd_nors_30
	s_nop 15
	s_nop 15
	v_mov_b32_e32 v21, v20
	s_nop 1
	v_permlane32_swap_b32_e32 v20, v21
	v_max_f32_e32 v20, v20, v21
	v_max_f32_e32 v20, v20, v20
	v_max_f32_e32 v170, 0, v20
	v_exp_f32_e64 v171, -v170
	v_add_f32_e32 v242, v242, v170
	v_xor_b32_e32 v82, 0x80000000, v242
	v_sub_f32_e32 v66, v23, v242
	v_mov_b32_e32 v83, v82
	v_mov_b32_e32 v67, v66
	v_mov_b32_e32 v84, v82
	v_mov_b32_e32 v68, v66
	v_mov_b32_e32 v85, v82
	v_mov_b32_e32 v69, v66
	v_mov_b32_e32 v86, v82
	v_mov_b32_e32 v70, v66
	v_mov_b32_e32 v87, v82
	v_mov_b32_e32 v71, v66
	v_mov_b32_e32 v88, v82
	v_mov_b32_e32 v72, v66
	v_mov_b32_e32 v89, v82
	v_mov_b32_e32 v73, v66
	v_mov_b32_e32 v90, v82
	v_mov_b32_e32 v74, v66
	v_mov_b32_e32 v91, v82
	v_mov_b32_e32 v75, v66
	v_mov_b32_e32 v92, v82
	v_mov_b32_e32 v76, v66
	v_mov_b32_e32 v93, v82
	v_mov_b32_e32 v77, v66
	v_mov_b32_e32 v94, v82
	v_mov_b32_e32 v78, v66
	v_mov_b32_e32 v95, v82
	v_mov_b32_e32 v79, v66
	v_mov_b32_e32 v96, v82
	v_mov_b32_e32 v80, v66
	v_mov_b32_e32 v97, v82
	v_mov_b32_e32 v81, v66
	v_sub_f32_e32 v114, v114, v170
	v_sub_f32_e32 v115, v115, v170
	v_sub_f32_e32 v116, v116, v170
	v_sub_f32_e32 v117, v117, v170
	v_sub_f32_e32 v118, v118, v170
	v_sub_f32_e32 v119, v119, v170
	v_sub_f32_e32 v120, v120, v170
	v_sub_f32_e32 v121, v121, v170
	v_sub_f32_e32 v122, v122, v170
	v_sub_f32_e32 v123, v123, v170
	v_sub_f32_e32 v124, v124, v170
	v_sub_f32_e32 v125, v125, v170
	v_sub_f32_e32 v126, v126, v170
	v_sub_f32_e32 v127, v127, v170
	v_sub_f32_e32 v128, v128, v170
	v_sub_f32_e32 v129, v129, v170
	v_sub_f32_e32 v130, v130, v170
	v_sub_f32_e32 v131, v131, v170
	v_sub_f32_e32 v132, v132, v170
	v_sub_f32_e32 v133, v133, v170
	v_sub_f32_e32 v134, v134, v170
	v_sub_f32_e32 v135, v135, v170
	v_sub_f32_e32 v136, v136, v170
	v_sub_f32_e32 v137, v137, v170
	v_sub_f32_e32 v138, v138, v170
	v_sub_f32_e32 v139, v139, v170
	v_sub_f32_e32 v140, v140, v170
	v_sub_f32_e32 v141, v141, v170
	v_sub_f32_e32 v142, v142, v170
	v_sub_f32_e32 v143, v143, v170
	v_sub_f32_e32 v144, v144, v170
	v_sub_f32_e32 v145, v145, v170
	v_mul_f32_e32 v240, v240, v171
	v_cmp_gt_u32_e32 vcc, 32, v233
	s_and_saveexec_b64 s[12:13], vcc
	ds_write_b32 v244, v171
	s_mov_b64 exec, s[12:13]
	ds_read_b128 v[174:177], v237 offset:0
	s_waitcnt lgkmcnt(0)
	v_mul_f32_e32 v50, v50, v174
	v_mul_f32_e32 v34, v34, v174
	v_mul_f32_e32 v51, v51, v175
	v_mul_f32_e32 v35, v35, v175
	v_mul_f32_e32 v52, v52, v176
	v_mul_f32_e32 v36, v36, v176
	v_mul_f32_e32 v53, v53, v177
	v_mul_f32_e32 v37, v37, v177
	ds_read_b128 v[174:177], v237 offset:32
	s_waitcnt lgkmcnt(0)
	v_mul_f32_e32 v54, v54, v174
	v_mul_f32_e32 v38, v38, v174
	v_mul_f32_e32 v55, v55, v175
	v_mul_f32_e32 v39, v39, v175
	v_mul_f32_e32 v56, v56, v176
	v_mul_f32_e32 v40, v40, v176
	v_mul_f32_e32 v57, v57, v177
	v_mul_f32_e32 v41, v41, v177
	ds_read_b128 v[174:177], v237 offset:64
	s_waitcnt lgkmcnt(0)
	v_mul_f32_e32 v58, v58, v174
	v_mul_f32_e32 v42, v42, v174
	v_mul_f32_e32 v59, v59, v175
	v_mul_f32_e32 v43, v43, v175
	v_mul_f32_e32 v60, v60, v176
	v_mul_f32_e32 v44, v44, v176
	v_mul_f32_e32 v61, v61, v177
	v_mul_f32_e32 v45, v45, v177
	ds_read_b128 v[174:177], v237 offset:96
	s_waitcnt lgkmcnt(0)
	v_mul_f32_e32 v62, v62, v174
	v_mul_f32_e32 v46, v46, v174
	v_mul_f32_e32 v63, v63, v175
	v_mul_f32_e32 v47, v47, v175
	v_mul_f32_e32 v64, v64, v176
	v_mul_f32_e32 v48, v48, v176
	v_mul_f32_e32 v65, v65, v177
	v_mul_f32_e32 v49, v49, v177

.Lbd_dk_33:
	s_add_i32 s10, s79, 0
	s_and_b32 s10, s10, 3
	s_lshl_b32 s10, s10, 13
	v_add_u32_e32 v2, s10, v241
	v_mfma_f32_32x32x16_bf16 v[162:177], v[194:197], v[146:149], v[82:97]
	v_exp_f32_e32 v114, v114
	v_exp_f32_e32 v115, v115
	v_exp_f32_e32 v116, v116
	v_add_f32_e32 v22, v114, v115
	v_exp_f32_e32 v117, v117
	ds_read_b64_tr_b16 v[98:99], v2 offset:49152
	ds_read_b64_tr_b16 v[100:101], v2 offset:49664
	ds_read_b64_tr_b16 v[102:103], v2 offset:50176
	ds_read_b64_tr_b16 v[104:105], v2 offset:50688
	v_mfma_f32_32x32x16_bf16 v[178:193], v[198:201], v[146:149], v[82:97]
	v_exp_f32_e32 v118, v118
	v_add_f32_e32 v22, v22, v116
	v_exp_f32_e32 v119, v119
	v_add_f32_e32 v22, v22, v117
	v_exp_f32_e32 v120, v120
	ds_read_b64_tr_b16 v[106:107], v2 offset:51200
	ds_read_b64_tr_b16 v[108:109], v2 offset:51712
	ds_read_b64_tr_b16 v[110:111], v2 offset:52224
	ds_read_b64_tr_b16 v[112:113], v2 offset:52736
	v_mfma_f32_32x32x16_bf16 v[162:177], v[202:205], v[150:153], v[162:177]
	v_add_f32_e32 v22, v22, v118
	v_exp_f32_e32 v121, v121
	v_add_f32_e32 v22, v22, v119
	v_add_f32_e32 v22, v22, v120
	v_add_f32_e32 v22, v22, v121
	ds_read_b64_tr_b16 v[4:5], v2 offset:53248
	ds_read_b64_tr_b16 v[6:7], v2 offset:53760
	ds_read_b64_tr_b16 v[8:9], v2 offset:54272
	ds_read_b64_tr_b16 v[10:11], v2 offset:54784
	v_mfma_f32_32x32x16_bf16 v[178:193], v[206:209], v[150:153], v[178:193]
	v_cvt_pk_bf16_f32 v114, v114, v115
	v_cvt_pk_bf16_f32 v115, v116, v117
	v_cvt_pk_bf16_f32 v116, v118, v119
	v_cvt_pk_bf16_f32 v117, v120, v121
	ds_read_b64_tr_b16 v[12:13], v2 offset:55296
	ds_read_b64_tr_b16 v[14:15], v2 offset:55808
	ds_read_b64_tr_b16 v[16:17], v2 offset:56320
	ds_read_b64_tr_b16 v[18:19], v2 offset:56832
	v_mfma_f32_32x32x16_bf16 v[162:177], v[210:213], v[154:157], v[162:177]
	v_exp_f32_e32 v122, v122
	v_exp_f32_e32 v123, v123
	v_exp_f32_e32 v124, v124
	v_add_f32_e32 v22, v22, v122
	v_exp_f32_e32 v125, v125
	v_mfma_f32_32x32x16_bf16 v[178:193], v[214:217], v[154:157], v[178:193]
	v_add_f32_e32 v22, v22, v123
	v_exp_f32_e32 v126, v126
	v_add_f32_e32 v22, v22, v124
	v_exp_f32_e32 v127, v127
	v_add_f32_e32 v22, v22, v125
	v_mfma_f32_32x32x16_bf16 v[162:177], v[218:221], v[158:161], v[162:177]
	v_exp_f32_e32 v128, v128
	v_add_f32_e32 v22, v22, v126
	v_exp_f32_e32 v129, v129
	v_add_f32_e32 v22, v22, v127
	v_add_f32_e32 v22, v22, v128
	v_mfma_f32_32x32x16_bf16 v[178:193], v[222:225], v[158:161], v[178:193]
	v_add_f32_e32 v22, v22, v129
	v_cvt_pk_bf16_f32 v122, v122, v123
	v_cvt_pk_bf16_f32 v123, v124, v125
	v_cvt_pk_bf16_f32 v124, v126, v127
	v_cvt_pk_bf16_f32 v125, v128, v129
	s_waitcnt lgkmcnt(0)
	s_add_i32 s10, s79, 2
	s_and_b32 s10, s10, 3
	s_mulk_i32 s10, 0x3000
	v_add_u32_e32 v2, s10, v239
	v_mfma_f32_32x32x16_bf16 v[50:65], v[114:117], v[98:101], v[50:65]
	v_exp_f32_e32 v130, v130
	v_exp_f32_e32 v131, v131
	v_exp_f32_e32 v132, v132
	v_add_f32_e32 v22, v22, v130
	v_exp_f32_e32 v133, v133
	v_add_f32_e32 v22, v22, v131
	v_exp_f32_e32 v134, v134
	v_add_f32_e32 v22, v22, v132
	v_exp_f32_e32 v135, v135
	v_add_f32_e32 v22, v22, v133
	ds_read_b128 v[194:197], v2
	ds_read_b128 v[198:201], v2 offset:512
	v_mfma_f32_32x32x16_bf16 v[34:49], v[114:117], v[4:7], v[34:49]
	v_exp_f32_e32 v136, v136
	v_add_f32_e32 v22, v22, v134
	v_exp_f32_e32 v137, v137
	v_add_f32_e32 v22, v22, v135
	v_add_f32_e32 v22, v22, v136
	v_add_f32_e32 v22, v22, v137
	v_cvt_pk_bf16_f32 v130, v130, v131
	v_cvt_pk_bf16_f32 v131, v132, v133
	v_cvt_pk_bf16_f32 v132, v134, v135
	v_cvt_pk_bf16_f32 v133, v136, v137
	ds_read_b128 v[202:205], v2 offset:2048
	ds_read_b128 v[206:209], v2 offset:2560
	v_mfma_f32_32x32x16_bf16 v[50:65], v[122:125], v[102:105], v[50:65]
	v_exp_f32_e32 v138, v138
	v_exp_f32_e32 v139, v139
	v_exp_f32_e32 v140, v140
	v_add_f32_e32 v22, v22, v138
	v_exp_f32_e32 v141, v141
	v_add_f32_e32 v22, v22, v139
	v_exp_f32_e32 v142, v142
	v_add_f32_e32 v22, v22, v140
	v_exp_f32_e32 v143, v143
	v_add_f32_e32 v22, v22, v141
	ds_read_b128 v[210:213], v2 offset:4096
	ds_read_b128 v[214:217], v2 offset:4608
	v_mfma_f32_32x32x16_bf16 v[34:49], v[122:125], v[8:11], v[34:49]
	v_exp_f32_e32 v144, v144
	v_add_f32_e32 v22, v22, v142
	v_exp_f32_e32 v145, v145
	v_add_f32_e32 v22, v22, v143
	v_add_f32_e32 v22, v22, v144
	v_add_f32_e32 v22, v22, v145
	v_cvt_pk_bf16_f32 v138, v138, v139
	v_cvt_pk_bf16_f32 v139, v140, v141
	v_cvt_pk_bf16_f32 v140, v142, v143
	v_cvt_pk_bf16_f32 v141, v144, v145
	v_add_f32_e32 v240, v240, v22
	ds_read_b128 v[218:221], v2 offset:6144
	ds_read_b128 v[222:225], v2 offset:6656
	v_mfma_f32_32x32x16_bf16 v[50:65], v[130:133], v[106:109], v[50:65]
	v_mfma_f32_32x32x16_bf16 v[34:49], v[130:133], v[12:15], v[34:49]
	v_mfma_f32_32x32x16_bf16 v[50:65], v[138:141], v[110:113], v[50:65]
	v_mfma_f32_32x32x16_bf16 v[34:49], v[138:141], v[16:19], v[34:49]
	ds_read2_b32 v[30:31], v29 offset0:123 offset1:122
	ds_read2_b32 v[32:33], v29 offset0:121 offset1:120
	ds_read2_b32 v[246:247], v29 offset0:115 offset1:114
	ds_read2_b32 v[248:249], v29 offset0:113 offset1:112
	s_waitcnt lgkmcnt(0)
	v_add_f32_e32 v162, v162, v30
	v_add_f32_e32 v163, v163, v31
	v_add_f32_e32 v164, v164, v32
	v_add_f32_e32 v165, v165, v33
	v_add_f32_e32 v166, v166, v246
	v_add_f32_e32 v167, v167, v247
	v_add_f32_e32 v168, v168, v248
	v_add_f32_e32 v169, v169, v249
	ds_read2_b32 v[30:31], v29 offset0:107 offset1:106
	ds_read2_b32 v[32:33], v29 offset0:105 offset1:104
	ds_read2_b32 v[246:247], v29 offset0:99 offset1:98
	ds_read2_b32 v[248:249], v29 offset0:97 offset1:96
	s_waitcnt lgkmcnt(0)
	v_add_f32_e32 v170, v170, v30
	v_add_f32_e32 v171, v171, v31
	v_add_f32_e32 v172, v172, v32
	v_add_f32_e32 v173, v173, v33
	v_add_f32_e32 v174, v174, v246
	v_add_f32_e32 v175, v175, v247
	v_add_f32_e32 v176, v176, v248
	v_add_f32_e32 v177, v177, v249
	ds_read2_b32 v[30:31], v29 offset0:91 offset1:90
	ds_read2_b32 v[32:33], v29 offset0:89 offset1:88
	ds_read2_b32 v[246:247], v29 offset0:83 offset1:82
	ds_read2_b32 v[248:249], v29 offset0:81 offset1:80
	s_waitcnt lgkmcnt(0)
	v_add_f32_e32 v178, v178, v30
	v_add_f32_e32 v179, v179, v31
	v_add_f32_e32 v180, v180, v32
	v_add_f32_e32 v181, v181, v33
	v_add_f32_e32 v182, v182, v246
	v_add_f32_e32 v183, v183, v247
	v_add_f32_e32 v184, v184, v248
	v_add_f32_e32 v185, v185, v249
	ds_read2_b32 v[30:31], v29 offset0:75 offset1:74
	ds_read2_b32 v[32:33], v29 offset0:73 offset1:72
	ds_read2_b32 v[246:247], v29 offset0:67 offset1:66
	ds_read2_b32 v[248:249], v29 offset0:65 offset1:64
	s_waitcnt lgkmcnt(0)
	v_add_f32_e32 v186, v186, v30
	v_add_f32_e32 v187, v187, v31
	v_add_f32_e32 v188, v188, v32
	v_add_f32_e32 v189, v189, v33
	v_add_f32_e32 v190, v190, v246
	v_add_f32_e32 v191, v191, v247
	v_add_f32_e32 v192, v192, v248
	v_add_f32_e32 v193, v193, v249
	v_max3_f32 v20, v162, v163, v164
	v_max3_f32 v21, v165, v166, v167
	v_max3_f32 v20, v20, v168, v169
	v_max3_f32 v21, v21, v170, v171
	v_max3_f32 v20, v20, v172, v173
	v_max3_f32 v21, v21, v174, v175
	v_max3_f32 v20, v20, v176, v177
	v_max3_f32 v21, v21, v178, v179
	v_max3_f32 v20, v20, v180, v181
	v_max3_f32 v21, v21, v182, v183
	v_max3_f32 v20, v20, v184, v185
	v_max3_f32 v21, v21, v186, v187
	v_max3_f32 v20, v20, v188, v189
	v_max3_f32 v21, v21, v190, v191
	v_max3_f32 v20, v20, v192, v193
	v_max_f32_e32 v20, v20, v21
	v_cmp_lt_f32_e32 vcc, s41, v20
	s_cbranch_vccz .Lbd_nors_34
	s_nop 15
	s_nop 15
	v_mov_b32_e32 v21, v20
	s_nop 1
	v_permlane32_swap_b32_e32 v20, v21
	v_max_f32_e32 v20, v20, v21
	v_max_f32_e32 v20, v20, v20
	v_max_f32_e32 v122, 0, v20
	v_exp_f32_e64 v123, -v122
	v_add_f32_e32 v242, v242, v122
	v_xor_b32_e32 v82, 0x80000000, v242
	v_sub_f32_e32 v66, v23, v242
	v_mov_b32_e32 v83, v82
	v_mov_b32_e32 v67, v66
	v_mov_b32_e32 v84, v82
	v_mov_b32_e32 v68, v66
	v_mov_b32_e32 v85, v82
	v_mov_b32_e32 v69, v66
	v_mov_b32_e32 v86, v82
	v_mov_b32_e32 v70, v66
	v_mov_b32_e32 v87, v82
	v_mov_b32_e32 v71, v66
	v_mov_b32_e32 v88, v82
	v_mov_b32_e32 v72, v66
	v_mov_b32_e32 v89, v82
	v_mov_b32_e32 v73, v66
	v_mov_b32_e32 v90, v82
	v_mov_b32_e32 v74, v66
	v_mov_b32_e32 v91, v82
	v_mov_b32_e32 v75, v66
	v_mov_b32_e32 v92, v82
	v_mov_b32_e32 v76, v66
	v_mov_b32_e32 v93, v82
	v_mov_b32_e32 v77, v66
	v_mov_b32_e32 v94, v82
	v_mov_b32_e32 v78, v66
	v_mov_b32_e32 v95, v82
	v_mov_b32_e32 v79, v66
	v_mov_b32_e32 v96, v82
	v_mov_b32_e32 v80, v66
	v_mov_b32_e32 v97, v82
	v_mov_b32_e32 v81, v66
	v_sub_f32_e32 v162, v162, v122
	v_sub_f32_e32 v163, v163, v122
	v_sub_f32_e32 v164, v164, v122
	v_sub_f32_e32 v165, v165, v122
	v_sub_f32_e32 v166, v166, v122
	v_sub_f32_e32 v167, v167, v122
	v_sub_f32_e32 v168, v168, v122
	v_sub_f32_e32 v169, v169, v122
	v_sub_f32_e32 v170, v170, v122
	v_sub_f32_e32 v171, v171, v122
	v_sub_f32_e32 v172, v172, v122
	v_sub_f32_e32 v173, v173, v122
	v_sub_f32_e32 v174, v174, v122
	v_sub_f32_e32 v175, v175, v122
	v_sub_f32_e32 v176, v176, v122
	v_sub_f32_e32 v177, v177, v122
	v_sub_f32_e32 v178, v178, v122
	v_sub_f32_e32 v179, v179, v122
	v_sub_f32_e32 v180, v180, v122
	v_sub_f32_e32 v181, v181, v122
	v_sub_f32_e32 v182, v182, v122
	v_sub_f32_e32 v183, v183, v122
	v_sub_f32_e32 v184, v184, v122
	v_sub_f32_e32 v185, v185, v122
	v_sub_f32_e32 v186, v186, v122
	v_sub_f32_e32 v187, v187, v122
	v_sub_f32_e32 v188, v188, v122
	v_sub_f32_e32 v189, v189, v122
	v_sub_f32_e32 v190, v190, v122
	v_sub_f32_e32 v191, v191, v122
	v_sub_f32_e32 v192, v192, v122
	v_sub_f32_e32 v193, v193, v122
	v_mul_f32_e32 v240, v240, v123
	v_cmp_gt_u32_e32 vcc, 32, v233
	s_and_saveexec_b64 s[12:13], vcc
	ds_write_b32 v244, v123
	s_mov_b64 exec, s[12:13]
	ds_read_b128 v[126:129], v237 offset:0
	s_waitcnt lgkmcnt(0)
	v_mul_f32_e32 v50, v50, v126
	v_mul_f32_e32 v34, v34, v126
	v_mul_f32_e32 v51, v51, v127
	v_mul_f32_e32 v35, v35, v127
	v_mul_f32_e32 v52, v52, v128
	v_mul_f32_e32 v36, v36, v128
	v_mul_f32_e32 v53, v53, v129
	v_mul_f32_e32 v37, v37, v129
	ds_read_b128 v[126:129], v237 offset:32
	s_waitcnt lgkmcnt(0)
	v_mul_f32_e32 v54, v54, v126
	v_mul_f32_e32 v38, v38, v126
	v_mul_f32_e32 v55, v55, v127
	v_mul_f32_e32 v39, v39, v127
	v_mul_f32_e32 v56, v56, v128
	v_mul_f32_e32 v40, v40, v128
	v_mul_f32_e32 v57, v57, v129
	v_mul_f32_e32 v41, v41, v129
	ds_read_b128 v[126:129], v237 offset:64
	s_waitcnt lgkmcnt(0)
	v_mul_f32_e32 v58, v58, v126
	v_mul_f32_e32 v42, v42, v126
	v_mul_f32_e32 v59, v59, v127
	v_mul_f32_e32 v43, v43, v127
	v_mul_f32_e32 v60, v60, v128
	v_mul_f32_e32 v44, v44, v128
	v_mul_f32_e32 v61, v61, v129
	v_mul_f32_e32 v45, v45, v129
	ds_read_b128 v[126:129], v237 offset:96
	s_waitcnt lgkmcnt(0)
	v_mul_f32_e32 v62, v62, v126
	v_mul_f32_e32 v46, v46, v126
	v_mul_f32_e32 v63, v63, v127
	v_mul_f32_e32 v47, v47, v127
	v_mul_f32_e32 v64, v64, v128
	v_mul_f32_e32 v48, v48, v128
	v_mul_f32_e32 v65, v65, v129
	v_mul_f32_e32 v49, v49, v129

.Lbd_dk_37:
	s_add_i32 s10, s79, 0
	s_and_b32 s10, s10, 3
	s_lshl_b32 s10, s10, 13
	v_add_u32_e32 v2, s10, v241
	v_mfma_f32_32x32x16_bf16 v[114:129], v[194:197], v[146:149], v[82:97]
	v_exp_f32_e32 v162, v162
	v_exp_f32_e32 v163, v163
	v_exp_f32_e32 v164, v164
	v_add_f32_e32 v22, v162, v163
	v_exp_f32_e32 v165, v165
	ds_read_b64_tr_b16 v[98:99], v2 offset:49152
	ds_read_b64_tr_b16 v[100:101], v2 offset:49664
	ds_read_b64_tr_b16 v[102:103], v2 offset:50176
	ds_read_b64_tr_b16 v[104:105], v2 offset:50688
	v_mfma_f32_32x32x16_bf16 v[130:145], v[198:201], v[146:149], v[82:97]
	v_exp_f32_e32 v166, v166
	v_add_f32_e32 v22, v22, v164
	v_exp_f32_e32 v167, v167
	v_add_f32_e32 v22, v22, v165
	v_exp_f32_e32 v168, v168
	ds_read_b64_tr_b16 v[106:107], v2 offset:51200
	ds_read_b64_tr_b16 v[108:109], v2 offset:51712
	ds_read_b64_tr_b16 v[110:111], v2 offset:52224
	ds_read_b64_tr_b16 v[112:113], v2 offset:52736
	v_mfma_f32_32x32x16_bf16 v[114:129], v[202:205], v[150:153], v[114:129]
	v_add_f32_e32 v22, v22, v166
	v_exp_f32_e32 v169, v169
	v_add_f32_e32 v22, v22, v167
	v_add_f32_e32 v22, v22, v168
	v_add_f32_e32 v22, v22, v169
	ds_read_b64_tr_b16 v[4:5], v2 offset:53248
	ds_read_b64_tr_b16 v[6:7], v2 offset:53760
	ds_read_b64_tr_b16 v[8:9], v2 offset:54272
	ds_read_b64_tr_b16 v[10:11], v2 offset:54784
	v_mfma_f32_32x32x16_bf16 v[130:145], v[206:209], v[150:153], v[130:145]
	v_cvt_pk_bf16_f32 v162, v162, v163
	v_cvt_pk_bf16_f32 v163, v164, v165
	v_cvt_pk_bf16_f32 v164, v166, v167
	v_cvt_pk_bf16_f32 v165, v168, v169
	ds_read_b64_tr_b16 v[12:13], v2 offset:55296
	ds_read_b64_tr_b16 v[14:15], v2 offset:55808
	ds_read_b64_tr_b16 v[16:17], v2 offset:56320
	ds_read_b64_tr_b16 v[18:19], v2 offset:56832
	v_mfma_f32_32x32x16_bf16 v[114:129], v[210:213], v[154:157], v[114:129]
	v_exp_f32_e32 v170, v170
	v_exp_f32_e32 v171, v171
	v_exp_f32_e32 v172, v172
	v_add_f32_e32 v22, v22, v170
	v_exp_f32_e32 v173, v173
	v_mfma_f32_32x32x16_bf16 v[130:145], v[214:217], v[154:157], v[130:145]
	v_add_f32_e32 v22, v22, v171
	v_exp_f32_e32 v174, v174
	v_add_f32_e32 v22, v22, v172
	v_exp_f32_e32 v175, v175
	v_add_f32_e32 v22, v22, v173
	v_mfma_f32_32x32x16_bf16 v[114:129], v[218:221], v[158:161], v[114:129]
	v_exp_f32_e32 v176, v176
	v_add_f32_e32 v22, v22, v174
	v_exp_f32_e32 v177, v177
	v_add_f32_e32 v22, v22, v175
	v_add_f32_e32 v22, v22, v176
	v_mfma_f32_32x32x16_bf16 v[130:145], v[222:225], v[158:161], v[130:145]
	v_add_f32_e32 v22, v22, v177
	v_cvt_pk_bf16_f32 v170, v170, v171
	v_cvt_pk_bf16_f32 v171, v172, v173
	v_cvt_pk_bf16_f32 v172, v174, v175
	v_cvt_pk_bf16_f32 v173, v176, v177
	s_waitcnt lgkmcnt(0)
	v_mfma_f32_32x32x16_bf16 v[50:65], v[162:165], v[98:101], v[50:65]
	v_exp_f32_e32 v178, v178
	v_exp_f32_e32 v179, v179
	v_exp_f32_e32 v180, v180
	v_add_f32_e32 v22, v22, v178
	v_exp_f32_e32 v181, v181
	v_add_f32_e32 v22, v22, v179
	v_exp_f32_e32 v182, v182
	v_add_f32_e32 v22, v22, v180
	v_exp_f32_e32 v183, v183
	v_add_f32_e32 v22, v22, v181
	v_mfma_f32_32x32x16_bf16 v[34:49], v[162:165], v[4:7], v[34:49]
	v_exp_f32_e32 v184, v184
	v_add_f32_e32 v22, v22, v182
	v_exp_f32_e32 v185, v185
	v_add_f32_e32 v22, v22, v183
	v_add_f32_e32 v22, v22, v184
	v_add_f32_e32 v22, v22, v185
	v_cvt_pk_bf16_f32 v178, v178, v179
	v_cvt_pk_bf16_f32 v179, v180, v181
	v_cvt_pk_bf16_f32 v180, v182, v183
	v_cvt_pk_bf16_f32 v181, v184, v185
	v_mfma_f32_32x32x16_bf16 v[50:65], v[170:173], v[102:105], v[50:65]
	v_exp_f32_e32 v186, v186
	v_exp_f32_e32 v187, v187
	v_exp_f32_e32 v188, v188
	v_add_f32_e32 v22, v22, v186
	v_exp_f32_e32 v189, v189
	v_add_f32_e32 v22, v22, v187
	v_exp_f32_e32 v190, v190
	v_add_f32_e32 v22, v22, v188
	v_exp_f32_e32 v191, v191
	v_add_f32_e32 v22, v22, v189
	v_mfma_f32_32x32x16_bf16 v[34:49], v[170:173], v[8:11], v[34:49]
	v_exp_f32_e32 v192, v192
	v_add_f32_e32 v22, v22, v190
	v_exp_f32_e32 v193, v193
	v_add_f32_e32 v22, v22, v191
	v_add_f32_e32 v22, v22, v192
	v_add_f32_e32 v22, v22, v193
	v_cvt_pk_bf16_f32 v186, v186, v187
	v_cvt_pk_bf16_f32 v187, v188, v189
	v_cvt_pk_bf16_f32 v188, v190, v191
	v_cvt_pk_bf16_f32 v189, v192, v193
	v_add_f32_e32 v240, v240, v22
	v_mfma_f32_32x32x16_bf16 v[50:65], v[178:181], v[106:109], v[50:65]
	v_mfma_f32_32x32x16_bf16 v[34:49], v[178:181], v[12:15], v[34:49]
	v_mfma_f32_32x32x16_bf16 v[50:65], v[186:189], v[110:113], v[50:65]
	v_mfma_f32_32x32x16_bf16 v[34:49], v[186:189], v[16:19], v[34:49]
	ds_read2_b32 v[30:31], v29 offset0:59 offset1:58
	ds_read2_b32 v[32:33], v29 offset0:57 offset1:56
	ds_read2_b32 v[246:247], v29 offset0:51 offset1:50
	ds_read2_b32 v[248:249], v29 offset0:49 offset1:48
	s_waitcnt lgkmcnt(0)
	v_add_f32_e32 v114, v114, v30
	v_add_f32_e32 v115, v115, v31
	v_add_f32_e32 v116, v116, v32
	v_add_f32_e32 v117, v117, v33
	v_add_f32_e32 v118, v118, v246
	v_add_f32_e32 v119, v119, v247
	v_add_f32_e32 v120, v120, v248
	v_add_f32_e32 v121, v121, v249
	ds_read2_b32 v[30:31], v29 offset0:43 offset1:42
	ds_read2_b32 v[32:33], v29 offset0:41 offset1:40
	ds_read2_b32 v[246:247], v29 offset0:35 offset1:34
	ds_read2_b32 v[248:249], v29 offset0:33 offset1:32
	s_waitcnt lgkmcnt(0)
	v_add_f32_e32 v122, v122, v30
	v_add_f32_e32 v123, v123, v31
	v_add_f32_e32 v124, v124, v32
	v_add_f32_e32 v125, v125, v33
	v_add_f32_e32 v126, v126, v246
	v_add_f32_e32 v127, v127, v247
	v_add_f32_e32 v128, v128, v248
	v_add_f32_e32 v129, v129, v249
	ds_read2_b32 v[30:31], v29 offset0:27 offset1:26
	ds_read2_b32 v[32:33], v29 offset0:25 offset1:24
	ds_read2_b32 v[246:247], v29 offset0:19 offset1:18
	ds_read2_b32 v[248:249], v29 offset0:17 offset1:16
	s_waitcnt lgkmcnt(0)
	v_add_f32_e32 v130, v130, v30
	v_add_f32_e32 v131, v131, v31
	v_add_f32_e32 v132, v132, v32
	v_add_f32_e32 v133, v133, v33
	v_add_f32_e32 v134, v134, v246
	v_add_f32_e32 v135, v135, v247
	v_add_f32_e32 v136, v136, v248
	v_add_f32_e32 v137, v137, v249
	ds_read2_b32 v[30:31], v29 offset0:11 offset1:10
	ds_read2_b32 v[32:33], v29 offset0:9 offset1:8
	ds_read2_b32 v[246:247], v29 offset0:3 offset1:2
	ds_read2_b32 v[248:249], v29 offset0:1 offset1:0
	s_waitcnt lgkmcnt(0)
	v_add_f32_e32 v138, v138, v30
	v_add_f32_e32 v139, v139, v31
	v_add_f32_e32 v140, v140, v32
	v_add_f32_e32 v141, v141, v33
	v_add_f32_e32 v142, v142, v246
	v_add_f32_e32 v143, v143, v247
	v_add_f32_e32 v144, v144, v248
	v_add_f32_e32 v145, v145, v249
	v_max3_f32 v20, v114, v115, v116
	v_max3_f32 v21, v117, v118, v119
	v_max3_f32 v20, v20, v120, v121
	v_max3_f32 v21, v21, v122, v123
	v_max3_f32 v20, v20, v124, v125
	v_max3_f32 v21, v21, v126, v127
	v_max3_f32 v20, v20, v128, v129
	v_max3_f32 v21, v21, v130, v131
	v_max3_f32 v20, v20, v132, v133
	v_max3_f32 v21, v21, v134, v135
	v_max3_f32 v20, v20, v136, v137
	v_max3_f32 v21, v21, v138, v139
	v_max3_f32 v20, v20, v140, v141
	v_max3_f32 v21, v21, v142, v143
	v_max3_f32 v20, v20, v144, v145
	v_max_f32_e32 v20, v20, v21
	v_cmp_lt_f32_e32 vcc, s41, v20
	s_cbranch_vccz .Lbd_nors_38
	s_nop 15
	s_nop 15
	v_mov_b32_e32 v21, v20
	s_nop 1
	v_permlane32_swap_b32_e32 v20, v21
	v_max_f32_e32 v20, v20, v21
	v_max_f32_e32 v20, v20, v20
	v_max_f32_e32 v170, 0, v20
	v_exp_f32_e64 v171, -v170
	v_add_f32_e32 v242, v242, v170
	v_xor_b32_e32 v82, 0x80000000, v242
	v_sub_f32_e32 v66, v23, v242
	v_mov_b32_e32 v83, v82
	v_mov_b32_e32 v67, v66
	v_mov_b32_e32 v84, v82
	v_mov_b32_e32 v68, v66
	v_mov_b32_e32 v85, v82
	v_mov_b32_e32 v69, v66
	v_mov_b32_e32 v86, v82
	v_mov_b32_e32 v70, v66
	v_mov_b32_e32 v87, v82
	v_mov_b32_e32 v71, v66
	v_mov_b32_e32 v88, v82
	v_mov_b32_e32 v72, v66
	v_mov_b32_e32 v89, v82
	v_mov_b32_e32 v73, v66
	v_mov_b32_e32 v90, v82
	v_mov_b32_e32 v74, v66
	v_mov_b32_e32 v91, v82
	v_mov_b32_e32 v75, v66
	v_mov_b32_e32 v92, v82
	v_mov_b32_e32 v76, v66
	v_mov_b32_e32 v93, v82
	v_mov_b32_e32 v77, v66
	v_mov_b32_e32 v94, v82
	v_mov_b32_e32 v78, v66
	v_mov_b32_e32 v95, v82
	v_mov_b32_e32 v79, v66
	v_mov_b32_e32 v96, v82
	v_mov_b32_e32 v80, v66
	v_mov_b32_e32 v97, v82
	v_mov_b32_e32 v81, v66
	v_sub_f32_e32 v114, v114, v170
	v_sub_f32_e32 v115, v115, v170
	v_sub_f32_e32 v116, v116, v170
	v_sub_f32_e32 v117, v117, v170
	v_sub_f32_e32 v118, v118, v170
	v_sub_f32_e32 v119, v119, v170
	v_sub_f32_e32 v120, v120, v170
	v_sub_f32_e32 v121, v121, v170
	v_sub_f32_e32 v122, v122, v170
	v_sub_f32_e32 v123, v123, v170
	v_sub_f32_e32 v124, v124, v170
	v_sub_f32_e32 v125, v125, v170
	v_sub_f32_e32 v126, v126, v170
	v_sub_f32_e32 v127, v127, v170
	v_sub_f32_e32 v128, v128, v170
	v_sub_f32_e32 v129, v129, v170
	v_sub_f32_e32 v130, v130, v170
	v_sub_f32_e32 v131, v131, v170
	v_sub_f32_e32 v132, v132, v170
	v_sub_f32_e32 v133, v133, v170
	v_sub_f32_e32 v134, v134, v170
	v_sub_f32_e32 v135, v135, v170
	v_sub_f32_e32 v136, v136, v170
	v_sub_f32_e32 v137, v137, v170
	v_sub_f32_e32 v138, v138, v170
	v_sub_f32_e32 v139, v139, v170
	v_sub_f32_e32 v140, v140, v170
	v_sub_f32_e32 v141, v141, v170
	v_sub_f32_e32 v142, v142, v170
	v_sub_f32_e32 v143, v143, v170
	v_sub_f32_e32 v144, v144, v170
	v_sub_f32_e32 v145, v145, v170
	v_mul_f32_e32 v240, v240, v171
	v_cmp_gt_u32_e32 vcc, 32, v233
	s_and_saveexec_b64 s[12:13], vcc
	ds_write_b32 v244, v171
	s_mov_b64 exec, s[12:13]
	ds_read_b128 v[174:177], v237 offset:0
	s_waitcnt lgkmcnt(0)
	v_mul_f32_e32 v50, v50, v174
	v_mul_f32_e32 v34, v34, v174
	v_mul_f32_e32 v51, v51, v175
	v_mul_f32_e32 v35, v35, v175
	v_mul_f32_e32 v52, v52, v176
	v_mul_f32_e32 v36, v36, v176
	v_mul_f32_e32 v53, v53, v177
	v_mul_f32_e32 v37, v37, v177
	ds_read_b128 v[174:177], v237 offset:32
	s_waitcnt lgkmcnt(0)
	v_mul_f32_e32 v54, v54, v174
	v_mul_f32_e32 v38, v38, v174
	v_mul_f32_e32 v55, v55, v175
	v_mul_f32_e32 v39, v39, v175
	v_mul_f32_e32 v56, v56, v176
	v_mul_f32_e32 v40, v40, v176
	v_mul_f32_e32 v57, v57, v177
	v_mul_f32_e32 v41, v41, v177
	ds_read_b128 v[174:177], v237 offset:64
	s_waitcnt lgkmcnt(0)
	v_mul_f32_e32 v58, v58, v174
	v_mul_f32_e32 v42, v42, v174
	v_mul_f32_e32 v59, v59, v175
	v_mul_f32_e32 v43, v43, v175
	v_mul_f32_e32 v60, v60, v176
	v_mul_f32_e32 v44, v44, v176
	v_mul_f32_e32 v61, v61, v177
	v_mul_f32_e32 v45, v45, v177
	ds_read_b128 v[174:177], v237 offset:96
	s_waitcnt lgkmcnt(0)
	v_mul_f32_e32 v62, v62, v174
	v_mul_f32_e32 v46, v46, v174
	v_mul_f32_e32 v63, v63, v175
	v_mul_f32_e32 v47, v47, v175
	v_mul_f32_e32 v64, v64, v176
	v_mul_f32_e32 v48, v48, v176
	v_mul_f32_e32 v65, v65, v177
	v_mul_f32_e32 v49, v49, v177

.Lbd_dk_41:
	s_add_i32 s10, s79, 0
	s_and_b32 s10, s10, 3
	s_lshl_b32 s10, s10, 13
	v_add_u32_e32 v2, s10, v241
	ds_read_b64_tr_b16 v[98:99], v2 offset:49152
	ds_read_b64_tr_b16 v[100:101], v2 offset:49664
	ds_read_b64_tr_b16 v[102:103], v2 offset:50176
	ds_read_b64_tr_b16 v[104:105], v2 offset:50688
	ds_read_b64_tr_b16 v[106:107], v2 offset:51200
	ds_read_b64_tr_b16 v[108:109], v2 offset:51712
	ds_read_b64_tr_b16 v[110:111], v2 offset:52224
	ds_read_b64_tr_b16 v[112:113], v2 offset:52736
	ds_read_b64_tr_b16 v[4:5], v2 offset:53248
	ds_read_b64_tr_b16 v[6:7], v2 offset:53760
	ds_read_b64_tr_b16 v[8:9], v2 offset:54272
	ds_read_b64_tr_b16 v[10:11], v2 offset:54784
	ds_read_b64_tr_b16 v[12:13], v2 offset:55296
	ds_read_b64_tr_b16 v[14:15], v2 offset:55808
	ds_read_b64_tr_b16 v[16:17], v2 offset:56320
	ds_read_b64_tr_b16 v[18:19], v2 offset:56832
	v_exp_f32_e32 v114, v114
	v_exp_f32_e32 v115, v115
	v_exp_f32_e32 v116, v116
	v_add_f32_e32 v22, v114, v115
	v_exp_f32_e32 v117, v117
	v_exp_f32_e32 v118, v118
	v_add_f32_e32 v22, v22, v116
	v_exp_f32_e32 v119, v119
	v_add_f32_e32 v22, v22, v117
	v_exp_f32_e32 v120, v120
	v_add_f32_e32 v22, v22, v118
	v_exp_f32_e32 v121, v121
	v_add_f32_e32 v22, v22, v119
	v_add_f32_e32 v22, v22, v120
	v_add_f32_e32 v22, v22, v121
	v_cvt_pk_bf16_f32 v114, v114, v115
	v_cvt_pk_bf16_f32 v115, v116, v117
	v_cvt_pk_bf16_f32 v116, v118, v119
	v_cvt_pk_bf16_f32 v117, v120, v121
	v_exp_f32_e32 v122, v122
	v_exp_f32_e32 v123, v123
	v_exp_f32_e32 v124, v124
	v_add_f32_e32 v22, v22, v122
	v_exp_f32_e32 v125, v125
	v_add_f32_e32 v22, v22, v123
	v_exp_f32_e32 v126, v126
	v_add_f32_e32 v22, v22, v124
	v_exp_f32_e32 v127, v127
	v_add_f32_e32 v22, v22, v125
	v_exp_f32_e32 v128, v128
	v_add_f32_e32 v22, v22, v126
	v_exp_f32_e32 v129, v129
	v_add_f32_e32 v22, v22, v127
	v_add_f32_e32 v22, v22, v128
	v_add_f32_e32 v22, v22, v129
	v_cvt_pk_bf16_f32 v122, v122, v123
	v_cvt_pk_bf16_f32 v123, v124, v125
	v_cvt_pk_bf16_f32 v124, v126, v127
	v_cvt_pk_bf16_f32 v125, v128, v129
	s_waitcnt lgkmcnt(0)
	v_mfma_f32_32x32x16_bf16 v[50:65], v[114:117], v[98:101], v[50:65]
	v_mfma_f32_32x32x16_bf16 v[34:49], v[114:117], v[4:7], v[34:49]
	v_exp_f32_e32 v130, v130
	v_exp_f32_e32 v131, v131
	v_exp_f32_e32 v132, v132
	v_add_f32_e32 v22, v22, v130
	v_exp_f32_e32 v133, v133
	v_add_f32_e32 v22, v22, v131
	v_exp_f32_e32 v134, v134
	v_add_f32_e32 v22, v22, v132
	v_exp_f32_e32 v135, v135
	v_add_f32_e32 v22, v22, v133
	v_exp_f32_e32 v136, v136
	v_add_f32_e32 v22, v22, v134
	v_exp_f32_e32 v137, v137
	v_add_f32_e32 v22, v22, v135
	v_add_f32_e32 v22, v22, v136
	v_add_f32_e32 v22, v22, v137
	v_cvt_pk_bf16_f32 v130, v130, v131
	v_cvt_pk_bf16_f32 v131, v132, v133
	v_cvt_pk_bf16_f32 v132, v134, v135
	v_cvt_pk_bf16_f32 v133, v136, v137
	v_mfma_f32_32x32x16_bf16 v[50:65], v[122:125], v[102:105], v[50:65]
	v_mfma_f32_32x32x16_bf16 v[34:49], v[122:125], v[8:11], v[34:49]
	v_exp_f32_e32 v138, v138
	v_exp_f32_e32 v139, v139
	v_exp_f32_e32 v140, v140
	v_add_f32_e32 v22, v22, v138
	v_exp_f32_e32 v141, v141
	v_add_f32_e32 v22, v22, v139
	v_exp_f32_e32 v142, v142
	v_add_f32_e32 v22, v22, v140
	v_exp_f32_e32 v143, v143
	v_add_f32_e32 v22, v22, v141
	v_exp_f32_e32 v144, v144
	v_add_f32_e32 v22, v22, v142
	v_exp_f32_e32 v145, v145
	v_add_f32_e32 v22, v22, v143
	v_add_f32_e32 v22, v22, v144
	v_add_f32_e32 v22, v22, v145
	v_cvt_pk_bf16_f32 v138, v138, v139
	v_cvt_pk_bf16_f32 v139, v140, v141
	v_cvt_pk_bf16_f32 v140, v142, v143
	v_cvt_pk_bf16_f32 v141, v144, v145
	v_add_f32_e32 v240, v240, v22
	s_nop 1
	v_mfma_f32_32x32x16_bf16 v[50:65], v[130:133], v[106:109], v[50:65]
	v_mfma_f32_32x32x16_bf16 v[34:49], v[130:133], v[12:15], v[34:49]
	v_mfma_f32_32x32x16_bf16 v[50:65], v[138:141], v[110:113], v[50:65]
	v_mfma_f32_32x32x16_bf16 v[34:49], v[138:141], v[16:19], v[34:49]
	s_add_i32 s79, s79, 1
	s_sub_i32 s81, 3, s80
	s_cmp_lt_i32 s81, 1
	s_cbranch_scc1 .Lbd_done

.Lbd_done:
	s_nop 15
	s_nop 3
	s_mov_b64 s[88:89], 0
	s_branch .LBB0_936
